# GEMM loops: B-fragment LDS base folded into ds_read immediates (no VALU at load-phase heads) on top of saddr DMA loads
# baseline (speedup 1.0000x reference)
; #define PG8_STAGE(bufoff, gbase, voff) do { _Pragma("unroll") for (int _i = 0; _i < 2; ++_i) \
;         __builtin_amdgcn_global_load_lds((const unsigned*)((const char*)(gbase) + (voff)[_i]), (PG8_LAS unsigned*)(lds + (bufoff) + ldsw + _i * 8192), 16, 0, 0); } while (0)
; #define PG8_WAIT_V(n) asm volatile("s_waitcnt vmcnt(" #n ")" ::: "memory")
; #define PG8_BAR __builtin_amdgcn_s_barrier()
; template <class Epi, class Sched, bool ALIGN_EPI = false, bool SP2 = false>
; __device__ __forceinline__ void gemm_phase(PG8_LAS unsigned char* lds, const Gemm g, const Sched& S, const Epi& E) {
;     ...
;     for (int i = 0; i < 2; ++i) { int R, C; stage_rc(tid * 16 + i * 8192, R, C); const int Rb = Epi::PERM ? ((R & ~31) + perm32(R & 31)) : R;
;         voffA[i] = (unsigned)(R * K + C) * 2u; voffB[i] = (unsigned)(Rb * K + C) * 2u; }
;     const size_t kstep = (size_t)(BK * 2);
;     const size_t hstep = (size_t)HALF * K * 2;
;     const size_t tstep = 2 * hstep;
;     const unsigned ldsw = (unsigned)wid * 1024u;
;     const int aoff = lds_byte(wr * 64 + fr, fq * 8), boff = lds_byte(wc * 32 + fr, fq * 8);
;     ...
;         PG8_STAGE(PG8_SB(1, 0), cB + kstep, voffB); PG8_STAGE(PG8_SA(1, 0), cA + kstep, voffA); PG8_STAGE(PG8_SB(1, 1), cB + hstep + kstep, voffB);
;         PG8_WAIT_V(6); PG8_BAR;
.LBB0_159:
	s_lshl_b32 s4, s21, 5
	s_and_b32 s37, s4, 0x60
	s_add_i32 m0, s45, 0x18000
	v_lshl_add_u64 v[6:7], v[6:7], 0, s[34:35]
	s_lshl_b32 s36, s17, 13
	s_lshl_b32 s21, s37, 7
	s_waitcnt vmcnt(2)
	s_barrier
	global_load_lds_dwordx4 v[6:7], off
	v_lshl_add_u64 v[6:7], v[8:9], 0, s[34:35]
	s_add_i32 m0, s45, 0x1a000
	s_add_i32 s4, s45, 0x8000
	s_add_i32 s52, s45, 0xa000
	global_load_lds_dwordx4 v[6:7], off
	v_lshl_add_u64 v[4:5], v[4:5], 0, s[34:35]
	s_mov_b32 m0, s4
	s_add_u32 s24, s28, 0x80080
	global_load_lds_dwordx4 v[4:5], off
	v_lshl_add_u64 v[4:5], v[10:11], 0, s[34:35]
	s_mov_b32 m0, s52
	s_addc_u32 s25, s29, 0
	global_load_lds_dwordx4 v[4:5], off
	s_add_i32 m0, s45, 0x1c000
	v_lshl_add_u64 v[4:5], s[24:25], 0, v[0:1]
	global_load_lds_dwordx4 v[4:5], off
	v_lshl_add_u64 v[4:5], s[24:25], 0, v[134:135]
	s_add_i32 m0, s45, 0x1e000
	v_and_b32_e32 v3, 15, v2
	global_load_lds_dwordx4 v[4:5], off
	v_bfe_u32 v4, v2, 4, 2
	v_lshlrev_b32_e32 v2, 4, v4
	v_lshlrev_b32_e32 v5, 2, v3
	v_lshl_or_b32 v160, s17, 6, v3
	v_lshl_or_b32 v2, v3, 6, v2
	v_and_b32_e32 v3, 32, v5
	v_bitop3_b32 v6, v2, s36, v3 bitop3:0xde
	v_bitop3_b32 v161, v2, s21, v3 bitop3:0xde
	v_add_u32_e32 v161, 0x10000, v161
	v_lshlrev_b32_e32 v2, 16, v4
	v_mov_b32_e32 v3, v1
	v_lshl_add_u64 v[140:141], s[22:23], 0, v[2:3]
	v_lshlrev_b32_e32 v2, 15, v16
	v_and_b32_e32 v2, 0xffff0000, v2
	v_lshl_add_u32 v2, v15, 12, v2
	v_and_b32_e32 v3, 1, v16
	v_lshl_or_b32 v2, v3, 6, v2
	s_cmpk_lt_u32 s20, 0x100
	v_lshl_add_u32 v142, v17, 1, v2
	v_lshlrev_b32_e32 v2, 15, v12
	s_cselect_b64 s[20:21], -1, 0
	s_lshl_b32 s17, s17, 8
	v_and_b32_e32 v2, 0xffff0000, v2
	s_waitcnt vmcnt(6)
	s_add_i32 s17, s17, 0
	v_lshl_add_u32 v2, v13, 12, v2
	v_and_b32_e32 v3, 1, v12
	s_add_i32 s17, s17, 0x23c00
	v_lshl_or_b32 v2, v3, 6, v2
	v_add_u32_e32 v162, s17, v5
	v_lshl_or_b32 v163, v4, 3, s37
	v_mov_b32_e32 v143, v1
	v_lshl_add_u32 v144, v14, 1, v2
	v_mov_b32_e32 v145, v1
	s_mov_b32 s53, 0
	v_add_u32_e32 v164, 0, v6
	s_barrier
	s_branch .LBB0_162

; #define PG8_STAGE(bufoff, gbase, voff) do { _Pragma("unroll") for (int _i = 0; _i < 2; ++_i) \
;         __builtin_amdgcn_global_load_lds((const unsigned*)((const char*)(gbase) + (voff)[_i]), (PG8_LAS unsigned*)(lds + (bufoff) + ldsw + _i * 8192), 16, 0, 0); } while (0)
; #define PG8_LDA(dst, b, h) do { _Pragma("unroll") for (int m = 0; m < 4; ++m) _Pragma("unroll") for (int k = 0; k < 2; ++k) dst[m][k] = *(const PG8_LAS bf16x8*)(lds + PG8_SA(b, h) + aoff + m * 2048 + k * 1024); } while (0)
; #define PG8_LDB(dst, b, h) do { _Pragma("unroll") for (int n = 0; n < 2; ++n) _Pragma("unroll") for (int k = 0; k < 2; ++k) dst[n][k] = *(const PG8_LAS bf16x8*)(lds + PG8_SB(b, h) + boff + n * 2048 + k * 1024); } while (0)
; #define PG8_MMA(ai, bj, At, Bt) do { __builtin_amdgcn_s_setprio(1); _Pragma("unroll") for (int m = 0; m < 4; ++m) _Pragma("unroll") for (int n = 0; n < 2; ++n) _Pragma("unroll") for (int k = 0; k < 2; ++k) \
;         acc[ai][bj][m][n] = __builtin_amdgcn_mfma_f32_16x16x32_bf16(Bt[n][k], At[m][k], acc[ai][bj][m][n], 0, 0, 0); __builtin_amdgcn_s_setprio(0); } while (0)
; #define PG8_WAIT_V(n) asm volatile("s_waitcnt vmcnt(" #n ")" ::: "memory")
; #define PG8_WAIT_L(n) asm volatile("s_waitcnt lgkmcnt(" #n ")" ::: "memory")
; template <class Epi, class Sched, bool ALIGN_EPI = false, bool SP2 = false>
; __device__ __forceinline__ void gemm_phase(PG8_LAS unsigned char* lds, const Gemm g, const Sched& S, const Epi& E) {
;     ...
;             const bool last = (t == nt - 2);
;             const char* a1 = cA + (size_t)(t + 1) * kstep;
;             const char* a2 = last ? nA : cA + (size_t)(t + 2) * kstep; const char* b2 = last ? nB : cB + (size_t)(t + 2) * kstep;
;             const char* a3 = a2 + kstep; const char* b3 = b2 + kstep;
;             if (last && has_next) S.a_ready(nxt);
;             if constexpr (SP2) {
;             PG8_LDB(B0, 0, 0); PG8_LDB(B1, 0, 1); PG8_SCHED; PG8_LDA(At, 0, 0); PG8_STAGE(PG8_SA(1, 1), a1 + hstep, voffA);
;             PG8_WAIT_V(8); PG8_WAIT_L(0); PG8_BAR; PG8_MMA(0, 0, At, B0); PG8_MMA(0, 1, At, B1); PG8_BAR; PG8_SCHED;
;             PG8_LDA(At, 0, 1); PG8_STAGE(PG8_SB(0, 0), b2, voffB); PG8_STAGE(PG8_SB(0, 1), b2 + hstep, voffB); PG8_STAGE(PG8_SA(0, 0), a2, voffA);
;             PG8_WAIT_V(8); PG8_WAIT_L(0); PG8_BAR; PG8_MMA(1, 0, At, B0); PG8_MMA(1, 1, At, B1); PG8_BAR; PG8_SCHED;
.LBB0_165:
	s_add_u32 s28, s26, 0xfff80080
	s_addc_u32 s29, s27, -1
	s_add_i32 s78, 0, 0x10000
	s_cmp_eq_u32 s77, 28
	s_cselect_b32 s41, s17, s29
	s_cselect_b32 s40, s25, s28
	s_cselect_b32 s29, s23, s73
	s_cselect_b32 s28, s54, s55
	s_add_i32 s80, 0, 0x14000
	ds_read_b128 v[130:133], v161
	ds_read_b128 v[146:149], v161 offset:1024
	ds_read_b128 v[150:153], v161 offset:2048
	ds_read_b128 v[154:157], v161 offset:3072
	ds_read_b128 v[180:183], v161 offset:16384
	ds_read_b128 v[184:187], v161 offset:17408
	ds_read_b128 v[188:191], v161 offset:18432
	ds_read_b128 v[192:195], v161 offset:19456
	s_add_i32 m0, s45, 0xc000
	ds_read_b128 v[196:199], v164
	ds_read_b128 v[200:203], v164 offset:1024
	ds_read_b128 v[218:221], v164 offset:2048
	ds_read_b128 v[222:225], v164 offset:3072
	ds_read_b128 v[226:229], v164 offset:4096
	ds_read_b128 v[230:233], v164 offset:5120
	ds_read_b128 v[234:237], v164 offset:6144
	ds_read_b128 v[238:241], v164 offset:7168
	global_load_lds_dwordx4 v142, s[26:27]
	s_add_i32 m0, s45, 0xe000
	s_nop 0
	global_load_lds_dwordx4 v144, s[26:27]
	s_waitcnt vmcnt(8)
	s_waitcnt lgkmcnt(0)
	s_barrier
	v_mfma_f32_16x16x32_bf16 v[126:129], v[130:133], v[196:199], v[126:129]
	v_mfma_f32_16x16x32_bf16 v[118:121], v[150:153], v[196:199], v[118:121]
	v_mfma_f32_16x16x32_bf16 v[110:113], v[130:133], v[218:221], v[110:113]
	v_mfma_f32_16x16x32_bf16 v[102:105], v[150:153], v[218:221], v[102:105]
	v_mfma_f32_16x16x32_bf16 v[94:97], v[130:133], v[226:229], v[94:97]
	v_mfma_f32_16x16x32_bf16 v[86:89], v[150:153], v[226:229], v[86:89]
	v_mfma_f32_16x16x32_bf16 v[78:81], v[130:133], v[234:237], v[78:81]
	v_mfma_f32_16x16x32_bf16 v[70:73], v[150:153], v[234:237], v[70:73]
	v_mfma_f32_16x16x32_bf16 v[126:129], v[146:149], v[200:203], v[126:129]
	v_mfma_f32_16x16x32_bf16 v[118:121], v[154:157], v[200:203], v[118:121]
	v_mfma_f32_16x16x32_bf16 v[110:113], v[146:149], v[222:225], v[110:113]
	v_mfma_f32_16x16x32_bf16 v[102:105], v[154:157], v[222:225], v[102:105]
	v_mfma_f32_16x16x32_bf16 v[94:97], v[146:149], v[230:233], v[94:97]
	v_mfma_f32_16x16x32_bf16 v[86:89], v[154:157], v[230:233], v[86:89]
	v_mfma_f32_16x16x32_bf16 v[78:81], v[146:149], v[238:241], v[78:81]
	v_mfma_f32_16x16x32_bf16 v[70:73], v[154:157], v[238:241], v[70:73]
	v_mfma_f32_16x16x32_bf16 v[122:125], v[180:183], v[196:199], v[122:125]
	v_mfma_f32_16x16x32_bf16 v[114:117], v[188:191], v[196:199], v[114:117]
	v_mfma_f32_16x16x32_bf16 v[106:109], v[180:183], v[218:221], v[106:109]
	v_mfma_f32_16x16x32_bf16 v[98:101], v[188:191], v[218:221], v[98:101]
	v_mfma_f32_16x16x32_bf16 v[90:93], v[180:183], v[226:229], v[90:93]
	v_mfma_f32_16x16x32_bf16 v[82:85], v[188:191], v[226:229], v[82:85]
	v_mfma_f32_16x16x32_bf16 v[74:77], v[180:183], v[234:237], v[74:77]
	v_mfma_f32_16x16x32_bf16 v[66:69], v[188:191], v[234:237], v[66:69]
	v_mfma_f32_16x16x32_bf16 v[122:125], v[184:187], v[200:203], v[122:125]
	v_mfma_f32_16x16x32_bf16 v[114:117], v[192:195], v[200:203], v[114:117]
	v_mfma_f32_16x16x32_bf16 v[106:109], v[184:187], v[222:225], v[106:109]
	v_mfma_f32_16x16x32_bf16 v[98:101], v[192:195], v[222:225], v[98:101]
	v_mfma_f32_16x16x32_bf16 v[90:93], v[184:187], v[230:233], v[90:93]
	v_mfma_f32_16x16x32_bf16 v[82:85], v[192:195], v[230:233], v[82:85]
	v_mfma_f32_16x16x32_bf16 v[74:77], v[184:187], v[238:241], v[74:77]
	v_mfma_f32_16x16x32_bf16 v[66:69], v[192:195], v[238:241], v[66:69]
	s_barrier
	s_add_i32 s78, s78, s46
	s_mov_b32 m0, s78
	ds_read_b128 v[196:199], v164 offset:16384
	ds_read_b128 v[200:203], v164 offset:17408
	ds_read_b128 v[218:221], v164 offset:18432
	ds_read_b128 v[222:225], v164 offset:19456
	ds_read_b128 v[226:229], v164 offset:20480
	ds_read_b128 v[230:233], v164 offset:21504
	ds_read_b128 v[234:237], v164 offset:22528
	ds_read_b128 v[238:241], v164 offset:23552
	global_load_lds_dwordx4 v0, s[28:29]
	s_add_i32 m0, s78, 0x2000
	s_add_u32 vcc_lo, s28, 0x80000
	v_lshl_add_u64 v[166:167], s[28:29], 0, v[134:135]
	s_addc_u32 vcc_hi, s29, 0
	s_add_i32 s78, s80, s46
	global_load_lds_dwordx4 v134, s[28:29]
	s_mov_b32 m0, s78
	v_lshl_add_u64 v[244:245], s[40:41], 0, v[136:137]
	global_load_lds_dwordx4 v0, vcc
	s_add_i32 m0, s78, 0x2000
	s_nop 0
	global_load_lds_dwordx4 v134, vcc
	v_lshl_add_u64 v[242:243], s[40:41], 0, v[138:139]
	s_mov_b32 m0, s45
	s_nop 0
	global_load_lds_dwordx4 v138, s[40:41]
	s_mov_b32 m0, s49
	s_nop 0
	global_load_lds_dwordx4 v136, s[40:41]
	s_waitcnt vmcnt(8)
	s_waitcnt lgkmcnt(0)
	s_barrier
	v_mfma_f32_16x16x32_bf16 v[62:65], v[130:133], v[196:199], v[62:65]
	v_mfma_f32_16x16x32_bf16 v[54:57], v[150:153], v[196:199], v[54:57]
	v_mfma_f32_16x16x32_bf16 v[46:49], v[130:133], v[218:221], v[46:49]
	v_mfma_f32_16x16x32_bf16 v[38:41], v[150:153], v[218:221], v[38:41]
	v_mfma_f32_16x16x32_bf16 v[30:33], v[130:133], v[226:229], v[30:33]
	v_mfma_f32_16x16x32_bf16 v[22:25], v[150:153], v[226:229], v[22:25]
	v_mfma_f32_16x16x32_bf16 v[14:17], v[130:133], v[234:237], v[14:17]
	v_mfma_f32_16x16x32_bf16 v[6:9], v[150:153], v[234:237], v[6:9]
	v_mfma_f32_16x16x32_bf16 v[62:65], v[146:149], v[200:203], v[62:65]
	v_mfma_f32_16x16x32_bf16 v[54:57], v[154:157], v[200:203], v[54:57]
	v_mfma_f32_16x16x32_bf16 v[46:49], v[146:149], v[222:225], v[46:49]
	v_mfma_f32_16x16x32_bf16 v[38:41], v[154:157], v[222:225], v[38:41]
	v_mfma_f32_16x16x32_bf16 v[30:33], v[146:149], v[230:233], v[30:33]
	v_mfma_f32_16x16x32_bf16 v[22:25], v[154:157], v[230:233], v[22:25]
	v_mfma_f32_16x16x32_bf16 v[14:17], v[146:149], v[238:241], v[14:17]
	v_mfma_f32_16x16x32_bf16 v[6:9], v[154:157], v[238:241], v[6:9]
	v_mfma_f32_16x16x32_bf16 v[58:61], v[180:183], v[196:199], v[58:61]
	v_mfma_f32_16x16x32_bf16 v[50:53], v[188:191], v[196:199], v[50:53]
	v_mfma_f32_16x16x32_bf16 v[42:45], v[180:183], v[218:221], v[42:45]
	v_mfma_f32_16x16x32_bf16 v[34:37], v[188:191], v[218:221], v[34:37]
	v_mfma_f32_16x16x32_bf16 v[26:29], v[180:183], v[226:229], v[26:29]
	v_mfma_f32_16x16x32_bf16 v[18:21], v[188:191], v[226:229], v[18:21]
	v_mfma_f32_16x16x32_bf16 v[10:13], v[180:183], v[234:237], v[10:13]
	v_mfma_f32_16x16x32_bf16 v[2:5], v[188:191], v[234:237], v[2:5]
	v_mfma_f32_16x16x32_bf16 v[58:61], v[184:187], v[200:203], v[58:61]
	v_mfma_f32_16x16x32_bf16 v[50:53], v[192:195], v[200:203], v[50:53]
	v_mfma_f32_16x16x32_bf16 v[42:45], v[184:187], v[222:225], v[42:45]
	v_mfma_f32_16x16x32_bf16 v[34:37], v[192:195], v[222:225], v[34:37]
	v_mfma_f32_16x16x32_bf16 v[26:29], v[184:187], v[230:233], v[26:29]
	v_mfma_f32_16x16x32_bf16 v[18:21], v[192:195], v[230:233], v[18:21]
	v_mfma_f32_16x16x32_bf16 v[10:13], v[184:187], v[238:241], v[10:13]
	v_mfma_f32_16x16x32_bf16 v[2:5], v[192:195], v[238:241], v[2:5]
	s_barrier
; #define PG8_STAGE(bufoff, gbase, voff) do { _Pragma("unroll") for (int _i = 0; _i < 2; ++_i) \
;         __builtin_amdgcn_global_load_lds((const unsigned*)((const char*)(gbase) + (voff)[_i]), (PG8_LAS unsigned*)(lds + (bufoff) + ldsw + _i * 8192), 16, 0, 0); } while (0)
; #define PG8_LDA(dst, b, h) do { _Pragma("unroll") for (int m = 0; m < 4; ++m) _Pragma("unroll") for (int k = 0; k < 2; ++k) dst[m][k] = *(const PG8_LAS bf16x8*)(lds + PG8_SA(b, h) + aoff + m * 2048 + k * 1024); } while (0)
; #define PG8_LDB(dst, b, h) do { _Pragma("unroll") for (int n = 0; n < 2; ++n) _Pragma("unroll") for (int k = 0; k < 2; ++k) dst[n][k] = *(const PG8_LAS bf16x8*)(lds + PG8_SB(b, h) + boff + n * 2048 + k * 1024); } while (0)
; #define PG8_MMA(ai, bj, At, Bt) do { __builtin_amdgcn_s_setprio(1); _Pragma("unroll") for (int m = 0; m < 4; ++m) _Pragma("unroll") for (int n = 0; n < 2; ++n) _Pragma("unroll") for (int k = 0; k < 2; ++k) \
;         acc[ai][bj][m][n] = __builtin_amdgcn_mfma_f32_16x16x32_bf16(Bt[n][k], At[m][k], acc[ai][bj][m][n], 0, 0, 0); __builtin_amdgcn_s_setprio(0); } while (0)
; #define PG8_WAIT_V(n) asm volatile("s_waitcnt vmcnt(" #n ")" ::: "memory")
; #define PG8_WAIT_L(n) asm volatile("s_waitcnt lgkmcnt(" #n ")" ::: "memory")
; #define PG8_BAR __builtin_amdgcn_s_barrier()
; #define PG8_SCHED __builtin_amdgcn_sched_barrier(0)
; template <class Epi, class Sched, bool ALIGN_EPI = false, bool SP2 = false>
; __device__ __forceinline__ void gemm_phase(PG8_LAS unsigned char* lds, const Gemm g, const Sched& S, const Epi& E) {
;     ...
;             PG8_LDB(B0, 1, 0); PG8_LDB(B1, 1, 1); PG8_SCHED; PG8_LDA(At, 1, 0); PG8_STAGE(PG8_SA(0, 1), a2 + hstep, voffA);
;             PG8_WAIT_V(8); PG8_WAIT_L(0); PG8_BAR; PG8_MMA(0, 0, At, B0); PG8_MMA(0, 1, At, B1); PG8_BAR; PG8_SCHED;
;             PG8_LDA(At, 1, 1); PG8_STAGE(PG8_SB(1, 0), b3, voffB); PG8_STAGE(PG8_SB(1, 1), b3 + hstep, voffB); PG8_STAGE(PG8_SA(1, 0), a3, voffA);
;             PG8_WAIT_V(8); PG8_WAIT_L(0); PG8_BAR; PG8_MMA(1, 0, At, B0); PG8_MMA(1, 1, At, B1); PG8_BAR; PG8_SCHED;
	s_add_i32 s78, 0, 0x18000
	s_add_i32 s80, 0, 0x1c000
	ds_read_b128 v[130:133], v161 offset:32768
	ds_read_b128 v[146:149], v161 offset:33792
	ds_read_b128 v[150:153], v161 offset:34816
	ds_read_b128 v[154:157], v161 offset:35840
	ds_read_b128 v[180:183], v161 offset:49152
	ds_read_b128 v[184:187], v161 offset:50176
	ds_read_b128 v[188:191], v161 offset:51200
	ds_read_b128 v[192:195], v161 offset:52224
	s_add_u32 s40, s40, 0x80000
	s_addc_u32 s41, s41, 0
	s_mov_b32 m0, s50
	ds_read_b128 v[196:199], v164 offset:32768
	ds_read_b128 v[200:203], v164 offset:33792
	ds_read_b128 v[218:221], v164 offset:34816
	ds_read_b128 v[222:225], v164 offset:35840
	ds_read_b128 v[226:229], v164 offset:36864
	ds_read_b128 v[230:233], v164 offset:37888
	ds_read_b128 v[234:237], v164 offset:38912
	ds_read_b128 v[238:241], v164 offset:39936
	global_load_lds_dwordx4 v138, s[40:41]
	s_mov_b32 m0, s51
	s_nop 0
	global_load_lds_dwordx4 v136, s[40:41]
	s_waitcnt vmcnt(8)
	s_waitcnt lgkmcnt(0)
	s_barrier
	v_mfma_f32_16x16x32_bf16 v[126:129], v[130:133], v[196:199], v[126:129]
	v_mfma_f32_16x16x32_bf16 v[118:121], v[150:153], v[196:199], v[118:121]
	v_mfma_f32_16x16x32_bf16 v[110:113], v[130:133], v[218:221], v[110:113]
	v_mfma_f32_16x16x32_bf16 v[102:105], v[150:153], v[218:221], v[102:105]
	v_mfma_f32_16x16x32_bf16 v[94:97], v[130:133], v[226:229], v[94:97]
	v_mfma_f32_16x16x32_bf16 v[86:89], v[150:153], v[226:229], v[86:89]
	v_mfma_f32_16x16x32_bf16 v[78:81], v[130:133], v[234:237], v[78:81]
	v_mfma_f32_16x16x32_bf16 v[70:73], v[150:153], v[234:237], v[70:73]
	v_mfma_f32_16x16x32_bf16 v[126:129], v[146:149], v[200:203], v[126:129]
	v_mfma_f32_16x16x32_bf16 v[118:121], v[154:157], v[200:203], v[118:121]
	v_mfma_f32_16x16x32_bf16 v[110:113], v[146:149], v[222:225], v[110:113]
	v_mfma_f32_16x16x32_bf16 v[102:105], v[154:157], v[222:225], v[102:105]
	v_mfma_f32_16x16x32_bf16 v[94:97], v[146:149], v[230:233], v[94:97]
	v_mfma_f32_16x16x32_bf16 v[86:89], v[154:157], v[230:233], v[86:89]
	v_mfma_f32_16x16x32_bf16 v[78:81], v[146:149], v[238:241], v[78:81]
	v_mfma_f32_16x16x32_bf16 v[70:73], v[154:157], v[238:241], v[70:73]
	v_mfma_f32_16x16x32_bf16 v[122:125], v[180:183], v[196:199], v[122:125]
	v_mfma_f32_16x16x32_bf16 v[114:117], v[188:191], v[196:199], v[114:117]
	v_mfma_f32_16x16x32_bf16 v[106:109], v[180:183], v[218:221], v[106:109]
	v_mfma_f32_16x16x32_bf16 v[98:101], v[188:191], v[218:221], v[98:101]
	v_mfma_f32_16x16x32_bf16 v[90:93], v[180:183], v[226:229], v[90:93]
	v_mfma_f32_16x16x32_bf16 v[82:85], v[188:191], v[226:229], v[82:85]
	v_mfma_f32_16x16x32_bf16 v[74:77], v[180:183], v[234:237], v[74:77]
	v_mfma_f32_16x16x32_bf16 v[66:69], v[188:191], v[234:237], v[66:69]
	v_mfma_f32_16x16x32_bf16 v[122:125], v[184:187], v[200:203], v[122:125]
	v_mfma_f32_16x16x32_bf16 v[114:117], v[192:195], v[200:203], v[114:117]
	v_mfma_f32_16x16x32_bf16 v[106:109], v[184:187], v[222:225], v[106:109]
	v_mfma_f32_16x16x32_bf16 v[98:101], v[192:195], v[222:225], v[98:101]
	v_mfma_f32_16x16x32_bf16 v[90:93], v[184:187], v[230:233], v[90:93]
	v_mfma_f32_16x16x32_bf16 v[82:85], v[192:195], v[230:233], v[82:85]
	v_mfma_f32_16x16x32_bf16 v[74:77], v[184:187], v[238:241], v[74:77]
	v_mfma_f32_16x16x32_bf16 v[66:69], v[192:195], v[238:241], v[66:69]
	s_barrier
	s_add_i32 s40, s78, s46
	s_add_i32 m0, s40, 0xffffff80
	ds_read_b128 v[196:199], v164 offset:49152
	ds_read_b128 v[200:203], v164 offset:50176
	ds_read_b128 v[218:221], v164 offset:51200
	ds_read_b128 v[222:225], v164 offset:52224
	ds_read_b128 v[226:229], v164 offset:53248
	ds_read_b128 v[230:233], v164 offset:54272
	ds_read_b128 v[234:237], v164 offset:55296
	ds_read_b128 v[238:241], v164 offset:56320
	global_load_lds_dwordx4 v0, s[28:29] offset:128
	s_add_i32 m0, s40, 0x2000
	s_add_u32 s28, s28, 0x80080
	v_lshl_add_u64 v[158:159], v[166:167], 0, s[34:35]
	s_addc_u32 s29, s29, 0
	s_add_i32 s40, s80, s46
	global_load_lds_dwordx4 v[158:159], off
	s_mov_b32 m0, s40
	s_nop 0
	global_load_lds_dwordx4 v0, s[28:29]
	s_add_i32 m0, s40, 0x2000
	s_nop 0
	global_load_lds_dwordx4 v134, s[28:29]
	v_lshl_add_u64 v[158:159], v[242:243], 0, s[34:35]
	s_mov_b32 m0, s4
	s_nop 0
	global_load_lds_dwordx4 v[158:159], off
	v_lshl_add_u64 v[158:159], v[244:245], 0, s[34:35]
	s_mov_b32 m0, s52
	s_nop 0
	global_load_lds_dwordx4 v[158:159], off
	s_waitcnt vmcnt(8)
	s_waitcnt lgkmcnt(0)
	s_barrier
	v_mfma_f32_16x16x32_bf16 v[62:65], v[130:133], v[196:199], v[62:65]
	v_mfma_f32_16x16x32_bf16 v[54:57], v[150:153], v[196:199], v[54:57]
	v_mfma_f32_16x16x32_bf16 v[46:49], v[130:133], v[218:221], v[46:49]
	v_mfma_f32_16x16x32_bf16 v[38:41], v[150:153], v[218:221], v[38:41]
	v_mfma_f32_16x16x32_bf16 v[30:33], v[130:133], v[226:229], v[30:33]
	v_mfma_f32_16x16x32_bf16 v[22:25], v[150:153], v[226:229], v[22:25]
	v_mfma_f32_16x16x32_bf16 v[14:17], v[130:133], v[234:237], v[14:17]
	v_mfma_f32_16x16x32_bf16 v[6:9], v[150:153], v[234:237], v[6:9]
	v_mfma_f32_16x16x32_bf16 v[62:65], v[146:149], v[200:203], v[62:65]
	v_mfma_f32_16x16x32_bf16 v[54:57], v[154:157], v[200:203], v[54:57]
	v_mfma_f32_16x16x32_bf16 v[46:49], v[146:149], v[222:225], v[46:49]
	v_mfma_f32_16x16x32_bf16 v[38:41], v[154:157], v[222:225], v[38:41]
	v_mfma_f32_16x16x32_bf16 v[30:33], v[146:149], v[230:233], v[30:33]
	v_mfma_f32_16x16x32_bf16 v[22:25], v[154:157], v[230:233], v[22:25]
	v_mfma_f32_16x16x32_bf16 v[14:17], v[146:149], v[238:241], v[14:17]
	v_mfma_f32_16x16x32_bf16 v[6:9], v[154:157], v[238:241], v[6:9]
	v_mfma_f32_16x16x32_bf16 v[58:61], v[180:183], v[196:199], v[58:61]
	v_mfma_f32_16x16x32_bf16 v[50:53], v[188:191], v[196:199], v[50:53]
	v_mfma_f32_16x16x32_bf16 v[42:45], v[180:183], v[218:221], v[42:45]
	v_mfma_f32_16x16x32_bf16 v[34:37], v[188:191], v[218:221], v[34:37]
	v_mfma_f32_16x16x32_bf16 v[26:29], v[180:183], v[226:229], v[26:29]
	v_mfma_f32_16x16x32_bf16 v[18:21], v[188:191], v[226:229], v[18:21]
	v_mfma_f32_16x16x32_bf16 v[10:13], v[180:183], v[234:237], v[10:13]
	v_mfma_f32_16x16x32_bf16 v[2:5], v[188:191], v[234:237], v[2:5]
	v_mfma_f32_16x16x32_bf16 v[58:61], v[184:187], v[200:203], v[58:61]
	v_mfma_f32_16x16x32_bf16 v[50:53], v[192:195], v[200:203], v[50:53]
	v_mfma_f32_16x16x32_bf16 v[42:45], v[184:187], v[222:225], v[42:45]
	v_mfma_f32_16x16x32_bf16 v[34:37], v[192:195], v[222:225], v[34:37]
	v_mfma_f32_16x16x32_bf16 v[26:29], v[184:187], v[230:233], v[26:29]
	v_mfma_f32_16x16x32_bf16 v[18:21], v[192:195], v[230:233], v[18:21]
	v_mfma_f32_16x16x32_bf16 v[10:13], v[184:187], v[238:241], v[10:13]
	v_mfma_f32_16x16x32_bf16 v[2:5], v[192:195], v[238:241], v[2:5]
	s_barrier
	s_add_i32 s77, s77, 2
	s_add_u32 s26, s26, 0x100
	s_addc_u32 s27, s27, 0
	s_add_u32 s55, s55, 0x100
	s_addc_u32 s73, s73, 0
	s_cmp_gt_u32 s77, 29
	s_cbranch_scc0 .LBB0_165
	s_and_b64 vcc, exec, s[20:21]
	s_cbranch_vccz .LBB0_168
	s_barrier

; #define PG8_WAIT_V(n) asm volatile("s_waitcnt vmcnt(" #n ")" ::: "memory")
; #define PG8_BAR __builtin_amdgcn_s_barrier()
; template <class Epi, class Sched, bool ALIGN_EPI = false, bool SP2 = false>
; __device__ __forceinline__ void gemm_phase(PG8_LAS unsigned char* lds, const Gemm g, const Sched& S, const Epi& E) {
;     ...
;     for (int i = 0; i < 2; ++i) { int R, C; stage_rc(tid * 16 + i * 8192, R, C); const int Rb = Epi::PERM ? ((R & ~31) + perm32(R & 31)) : R;
;         voffA[i] = (unsigned)(R * K + C) * 2u; voffB[i] = (unsigned)(Rb * K + C) * 2u; }
;     const size_t kstep = (size_t)(BK * 2);
;     const size_t hstep = (size_t)HALF * K * 2;
;     const size_t tstep = 2 * hstep;
;     const unsigned ldsw = (unsigned)wid * 1024u;
;     const int aoff = lds_byte(wr * 64 + fr, fq * 8), boff = lds_byte(wc * 32 + fr, fq * 8);
;     ...
;     Unit cur, nxt; int ui = 0;
;     if (!S.next(0, cur)) return;
;     f32x4 acc[2][2][4][2];
; #pragma unroll
;     for (int a = 0; a < 2; ++a)
; #pragma unroll
;         for (int b = 0; b < 2; ++b)
; #pragma unroll
;             for (int m = 0; m < 4; ++m)
; #pragma unroll
;                 for (int n = 0; n < 2; ++n) acc[a][b][m][n] = (f32x4){0.f, 0.f, 0.f, 0.f};
;     bf16x8 At[4][2], B0[2][2], B1[2][2];
;     const char* cA = (const char*)(cur.part ? g.A1 : g.A) + (size_t)cur.pm * tstep; const char* cB = (const char*)(cur.part ? g.Bt1 : g.Bt) + (size_t)cur.pn * tstep;
;     S.a_ready(cur);
;     if constexpr (SP2) {
;         PG8_STAGE(PG8_SB(0, 0), cB, voffB); PG8_STAGE(PG8_SB(0, 1), cB + hstep, voffB); PG8_STAGE(PG8_SA(0, 0), cA, voffA); PG8_STAGE(PG8_SA(0, 1), cA + hstep, voffA);
;         E.after_first_stage(tid);
;         if (wr == 1) PG8_BAR;
;         PG8_WAIT_V(2); PG8_BAR;
;         PG8_STAGE(PG8_SB(1, 0), cB + kstep, voffB); PG8_STAGE(PG8_SA(1, 0), cA + kstep, voffA); PG8_STAGE(PG8_SB(1, 1), cB + hstep + kstep, voffB);
;         PG8_WAIT_V(6); PG8_BAR;
;     } else {
;         PG8_STAGE(PG8_SB(0, 0), cB, voffB); PG8_STAGE(PG8_SA(0, 0), cA, voffA); PG8_STAGE(PG8_SB(0, 1), cB + hstep, voffB); PG8_STAGE(PG8_SA(0, 1), cA + hstep, voffA);
;         if (wr == 1) PG8_BAR;
;         PG8_WAIT_V(4); PG8_BAR;
;         PG8_STAGE(PG8_SB(1, 0), cB + kstep, voffB); PG8_STAGE(PG8_SA(1, 0), cA + kstep, voffA); PG8_STAGE(PG8_SB(1, 1), cB + hstep + kstep, voffB);
;         PG8_WAIT_V(6); PG8_BAR;
;     }
.LBB0_419:
	s_lshl_b32 s18, s18, 5
	s_and_b32 s18, s18, 0x60
	s_lshl_b32 s19, s17, 13
	s_lshl_b32 s20, s18, 7
	v_readlane_b32 s21, v250, 46
	v_readlane_b32 s22, v248, 20
	s_add_u32 s45, s21, s6
	v_readlane_b32 s6, v250, 47
	v_mov_b32_e32 v187, v1
	v_readlane_b32 s23, v248, 21
	s_addc_u32 s46, s6, s7
	s_add_i32 m0, s37, 0x18000
	v_lshl_add_u64 v[2:3], v[2:3], 0, s[34:35]
	v_lshl_add_u64 v[12:13], s[22:23], 0, v[186:187]
	v_mov_b32_e32 v183, v1
	s_waitcnt vmcnt(2)
	s_barrier
	global_load_lds_dwordx4 v[2:3], off
	v_lshl_add_u64 v[2:3], v[4:5], 0, s[34:35]
	s_add_i32 m0, s37, 0x1a000
	s_add_i32 s47, s37, 0x8000
	s_add_i32 s48, s37, 0xa000
	v_lshl_add_u64 v[14:15], s[22:23], 0, v[182:183]
	global_load_lds_dwordx4 v[2:3], off
	v_lshl_add_u64 v[2:3], v[12:13], 0, s[34:35]
	s_mov_b32 m0, s47
	s_add_u32 s6, s26, 0x40080
	global_load_lds_dwordx4 v[2:3], off
	v_lshl_add_u64 v[2:3], v[14:15], 0, s[34:35]
	s_mov_b32 m0, s48
	s_addc_u32 s7, s27, 0
	global_load_lds_dwordx4 v[2:3], off
	s_add_i32 m0, s37, 0x1c000
	v_lshl_add_u64 v[2:3], s[6:7], 0, v[184:185]
	global_load_lds_dwordx4 v[2:3], off
	v_lshl_add_u64 v[2:3], s[6:7], 0, v[180:181]
	s_add_i32 m0, s37, 0x1e000
	s_cmpk_lt_u32 s16, 0x100
	global_load_lds_dwordx4 v[2:3], off
	v_lshrrev_b32_e32 v3, 1, v6
	v_and_b32_e32 v3, 24, v3
	v_and_b32_e32 v2, 15, v6
	v_lshlrev_b32_e32 v4, 1, v3
	v_lshl_or_b32 v217, s17, 6, v2
	v_lshl_or_b32 v2, v2, 6, v4
	v_lshlrev_b32_e32 v4, 2, v6
	v_and_b32_e32 v4, 32, v4
	v_bitop3_b32 v5, v2, s19, v4 bitop3:0xde
	v_bitop3_b32 v218, v2, s20, v4 bitop3:0xde
	v_add_u32_e32 v218, 0x10000, v218
	v_lshlrev_b32_e32 v2, 14, v10
	v_and_b32_e32 v2, 0xffff8000, v2
	v_or_b32_e32 v219, s18, v3
	v_lshl_add_u32 v2, v9, 11, v2
	v_and_b32_e32 v3, 1, v10
	v_lshl_or_b32 v2, v3, 6, v2
	v_lshl_add_u32 v188, v11, 1, v2
	v_lshlrev_b32_e32 v2, 14, v0
	v_and_b32_e32 v2, 0xffff8000, v2
	v_lshl_add_u32 v2, v7, 11, v2
	v_and_b32_e32 v0, 1, v0
	s_waitcnt vmcnt(6)
	v_lshl_or_b32 v0, v0, 6, v2
	v_mov_b32_e32 v2, v1
	v_mov_b32_e32 v3, v1
	v_readlane_b32 s16, v248, 30
	v_lshl_add_u32 v190, v8, 1, v0
	v_mov_b32_e32 v0, v1
	v_add_u32_e32 v220, 0, v5
	v_mov_b64_e32 v[6:7], v[2:3]
	v_mov_b64_e32 v[10:11], v[2:3]
	v_mov_b64_e32 v[22:23], v[2:3]
	v_mov_b64_e32 v[26:27], v[2:3]
	v_mov_b64_e32 v[38:39], v[2:3]
	v_mov_b64_e32 v[42:43], v[2:3]
	v_mov_b64_e32 v[62:63], v[2:3]
	v_mov_b64_e32 v[66:67], v[2:3]
	v_mov_b64_e32 v[14:15], v[2:3]
	s_waitcnt lgkmcnt(0)
	v_mov_b64_e32 v[18:19], v[2:3]
	v_mov_b64_e32 v[30:31], v[2:3]
	v_mov_b64_e32 v[34:35], v[2:3]
	v_mov_b64_e32 v[46:47], v[2:3]
	v_mov_b64_e32 v[50:51], v[2:3]
	v_mov_b64_e32 v[70:71], v[2:3]
	v_mov_b64_e32 v[74:75], v[2:3]
	v_mov_b64_e32 v[78:79], v[2:3]
	v_mov_b64_e32 v[82:83], v[2:3]
	v_mov_b64_e32 v[114:115], v[2:3]
	v_mov_b64_e32 v[118:119], v[2:3]
	v_mov_b64_e32 v[142:143], v[2:3]
	v_mov_b64_e32 v[146:147], v[2:3]
	v_mov_b64_e32 v[158:159], v[2:3]
	v_mov_b64_e32 v[162:163], v[2:3]
	v_mov_b64_e32 v[102:103], v[2:3]
	v_mov_b64_e32 v[106:107], v[2:3]
	v_mov_b64_e32 v[134:135], v[2:3]
	v_mov_b64_e32 v[138:139], v[2:3]
	v_mov_b64_e32 v[110:111], v[2:3]
	v_mov_b64_e32 v[122:123], v[2:3]
	v_mov_b64_e32 v[86:87], v[2:3]
	v_mov_b64_e32 v[90:91], v[2:3]
	v_readlane_b32 s17, v248, 31
	s_cselect_b64 s[6:7], -1, 0
	v_mov_b32_e32 v189, v1
	v_mov_b32_e32 v191, v1
	s_mov_b32 s42, 0
	v_mov_b64_e32 v[4:5], v[0:1]
	v_mov_b64_e32 v[8:9], v[0:1]
	v_mov_b64_e32 v[20:21], v[0:1]
	v_mov_b64_e32 v[24:25], v[0:1]
	v_mov_b64_e32 v[36:37], v[0:1]
	v_mov_b64_e32 v[40:41], v[0:1]
	v_mov_b64_e32 v[60:61], v[0:1]
	v_mov_b64_e32 v[64:65], v[0:1]
	v_mov_b64_e32 v[12:13], v[0:1]
	v_mov_b64_e32 v[16:17], v[0:1]
	v_mov_b64_e32 v[28:29], v[0:1]
	v_mov_b64_e32 v[32:33], v[0:1]
	v_mov_b64_e32 v[44:45], v[0:1]
	v_mov_b64_e32 v[48:49], v[0:1]
	v_mov_b64_e32 v[68:69], v[0:1]
	v_mov_b64_e32 v[72:73], v[0:1]
	v_mov_b64_e32 v[76:77], v[0:1]
	v_mov_b64_e32 v[80:81], v[0:1]
	v_mov_b64_e32 v[112:113], v[0:1]
	v_mov_b64_e32 v[116:117], v[0:1]
	v_mov_b64_e32 v[140:141], v[0:1]
	v_mov_b64_e32 v[144:145], v[0:1]
	v_mov_b64_e32 v[156:157], v[0:1]
	v_mov_b64_e32 v[160:161], v[0:1]
	v_mov_b64_e32 v[100:101], v[0:1]
	v_mov_b64_e32 v[104:105], v[0:1]
	v_mov_b64_e32 v[132:133], v[0:1]
	v_mov_b64_e32 v[136:137], v[0:1]
	v_mov_b64_e32 v[108:109], v[0:1]
	v_mov_b64_e32 v[120:121], v[0:1]
	v_mov_b64_e32 v[84:85], v[0:1]
	v_mov_b64_e32 v[88:89], v[0:1]
	v_readlane_b32 s43, v248, 11
	s_mov_b32 s51, s16
	s_mov_b64 s[16:17], s[22:23]
	s_mov_b32 s49, 0
	s_barrier
	s_branch .LBB0_422

; #define PG8_STAGE(bufoff, gbase, voff) do { _Pragma("unroll") for (int _i = 0; _i < 2; ++_i) \
;         __builtin_amdgcn_global_load_lds((const unsigned*)((const char*)(gbase) + (voff)[_i]), (PG8_LAS unsigned*)(lds + (bufoff) + ldsw + _i * 8192), 16, 0, 0); } while (0)
; #define PG8_LDA(dst, b, h) do { _Pragma("unroll") for (int m = 0; m < 4; ++m) _Pragma("unroll") for (int k = 0; k < 2; ++k) dst[m][k] = *(const PG8_LAS bf16x8*)(lds + PG8_SA(b, h) + aoff + m * 2048 + k * 1024); } while (0)
; #define PG8_LDB(dst, b, h) do { _Pragma("unroll") for (int n = 0; n < 2; ++n) _Pragma("unroll") for (int k = 0; k < 2; ++k) dst[n][k] = *(const PG8_LAS bf16x8*)(lds + PG8_SB(b, h) + boff + n * 2048 + k * 1024); } while (0)
; #define PG8_MMA(ai, bj, At, Bt) do { __builtin_amdgcn_s_setprio(1); _Pragma("unroll") for (int m = 0; m < 4; ++m) _Pragma("unroll") for (int n = 0; n < 2; ++n) _Pragma("unroll") for (int k = 0; k < 2; ++k) \
;         acc[ai][bj][m][n] = __builtin_amdgcn_mfma_f32_16x16x32_bf16(Bt[n][k], At[m][k], acc[ai][bj][m][n], 0, 0, 0); __builtin_amdgcn_s_setprio(0); } while (0)
; #define PG8_WAIT_V(n) asm volatile("s_waitcnt vmcnt(" #n ")" ::: "memory")
; #define PG8_WAIT_L(n) asm volatile("s_waitcnt lgkmcnt(" #n ")" ::: "memory")
; template <class Epi, class Sched, bool ALIGN_EPI = false, bool SP2 = false>
; __device__ __forceinline__ void gemm_phase(PG8_LAS unsigned char* lds, const Gemm g, const Sched& S, const Epi& E) {
;     ...
;             const bool last = (t == nt - 2);
;             const char* a1 = cA + (size_t)(t + 1) * kstep;
;             const char* a2 = last ? nA : cA + (size_t)(t + 2) * kstep; const char* b2 = last ? nB : cB + (size_t)(t + 2) * kstep;
;             const char* a3 = a2 + kstep; const char* b3 = b2 + kstep;
;             if (last && has_next) S.a_ready(nxt);
;             if constexpr (SP2) {
;             PG8_LDB(B0, 0, 0); PG8_LDB(B1, 0, 1); PG8_SCHED; PG8_LDA(At, 0, 0); PG8_STAGE(PG8_SA(1, 1), a1 + hstep, voffA);
;             PG8_WAIT_V(8); PG8_WAIT_L(0); PG8_BAR; PG8_MMA(0, 0, At, B0); PG8_MMA(0, 1, At, B1); PG8_BAR; PG8_SCHED;
;             PG8_LDA(At, 0, 1); PG8_STAGE(PG8_SB(0, 0), b2, voffB); PG8_STAGE(PG8_SB(0, 1), b2 + hstep, voffB); PG8_STAGE(PG8_SA(0, 0), a2, voffA);
;             PG8_WAIT_V(8); PG8_WAIT_L(0); PG8_BAR; PG8_MMA(1, 0, At, B0); PG8_MMA(1, 1, At, B1); PG8_BAR; PG8_SCHED;
.LBB0_429:
	s_add_u32 s26, s16, 0xfffc0080
	s_addc_u32 s27, s17, -1
	s_add_i32 s54, 0, 0x10000
	s_cmp_eq_u32 s78, 12
	s_cselect_b32 s29, s21, s27
	s_cselect_b32 s28, s52, s26
	s_cselect_b32 s27, s19, s77
	s_cselect_b32 s26, s53, s73
	s_add_i32 s55, 0, 0x14000
	ds_read_b128 v[52:55], v218
	ds_read_b128 v[56:59], v218 offset:1024
	ds_read_b128 v[92:95], v218 offset:2048
	ds_read_b128 v[96:99], v218 offset:3072
	ds_read_b128 v[124:127], v218 offset:16384
	ds_read_b128 v[128:131], v218 offset:17408
	ds_read_b128 v[148:151], v218 offset:18432
	ds_read_b128 v[152:155], v218 offset:19456
	s_add_i32 m0, s37, 0xc000
	ds_read_b128 v[164:167], v220
	ds_read_b128 v[192:195], v220 offset:1024
	ds_read_b128 v[196:199], v220 offset:2048
	ds_read_b128 v[200:203], v220 offset:3072
	ds_read_b128 v[222:225], v220 offset:4096
	ds_read_b128 v[226:229], v220 offset:5120
	ds_read_b128 v[230:233], v220 offset:6144
	ds_read_b128 v[234:237], v220 offset:7168
	global_load_lds_dwordx4 v188, s[16:17]
	s_add_i32 m0, s37, 0xe000
	s_nop 0
	global_load_lds_dwordx4 v190, s[16:17]
	s_waitcnt vmcnt(8)
	s_waitcnt lgkmcnt(0)
	s_barrier
	v_mfma_f32_16x16x32_bf16 v[88:91], v[52:55], v[164:167], v[88:91]
	v_mfma_f32_16x16x32_bf16 v[84:87], v[92:95], v[164:167], v[84:87]
	v_mfma_f32_16x16x32_bf16 v[120:123], v[52:55], v[196:199], v[120:123]
	v_mfma_f32_16x16x32_bf16 v[108:111], v[92:95], v[196:199], v[108:111]
	v_mfma_f32_16x16x32_bf16 v[136:139], v[52:55], v[222:225], v[136:139]
	v_mfma_f32_16x16x32_bf16 v[132:135], v[92:95], v[222:225], v[132:135]
	v_mfma_f32_16x16x32_bf16 v[104:107], v[52:55], v[230:233], v[104:107]
	v_mfma_f32_16x16x32_bf16 v[100:103], v[92:95], v[230:233], v[100:103]
	v_mfma_f32_16x16x32_bf16 v[88:91], v[56:59], v[192:195], v[88:91]
	v_mfma_f32_16x16x32_bf16 v[84:87], v[96:99], v[192:195], v[84:87]
	v_mfma_f32_16x16x32_bf16 v[120:123], v[56:59], v[200:203], v[120:123]
	v_mfma_f32_16x16x32_bf16 v[108:111], v[96:99], v[200:203], v[108:111]
	v_mfma_f32_16x16x32_bf16 v[136:139], v[56:59], v[226:229], v[136:139]
	v_mfma_f32_16x16x32_bf16 v[132:135], v[96:99], v[226:229], v[132:135]
	v_mfma_f32_16x16x32_bf16 v[104:107], v[56:59], v[234:237], v[104:107]
	v_mfma_f32_16x16x32_bf16 v[100:103], v[96:99], v[234:237], v[100:103]
	v_mfma_f32_16x16x32_bf16 v[160:163], v[124:127], v[164:167], v[160:163]
	v_mfma_f32_16x16x32_bf16 v[156:159], v[148:151], v[164:167], v[156:159]
	v_mfma_f32_16x16x32_bf16 v[144:147], v[124:127], v[196:199], v[144:147]
	v_mfma_f32_16x16x32_bf16 v[140:143], v[148:151], v[196:199], v[140:143]
	v_mfma_f32_16x16x32_bf16 v[116:119], v[124:127], v[222:225], v[116:119]
	v_mfma_f32_16x16x32_bf16 v[112:115], v[148:151], v[222:225], v[112:115]
	v_mfma_f32_16x16x32_bf16 v[80:83], v[124:127], v[230:233], v[80:83]
	v_mfma_f32_16x16x32_bf16 v[76:79], v[148:151], v[230:233], v[76:79]
	v_mfma_f32_16x16x32_bf16 v[160:163], v[128:131], v[192:195], v[160:163]
	v_mfma_f32_16x16x32_bf16 v[156:159], v[152:155], v[192:195], v[156:159]
	v_mfma_f32_16x16x32_bf16 v[144:147], v[128:131], v[200:203], v[144:147]
	v_mfma_f32_16x16x32_bf16 v[140:143], v[152:155], v[200:203], v[140:143]
	v_mfma_f32_16x16x32_bf16 v[116:119], v[128:131], v[226:229], v[116:119]
	v_mfma_f32_16x16x32_bf16 v[112:115], v[152:155], v[226:229], v[112:115]
	v_mfma_f32_16x16x32_bf16 v[80:83], v[128:131], v[234:237], v[80:83]
	v_mfma_f32_16x16x32_bf16 v[76:79], v[152:155], v[234:237], v[76:79]
	s_barrier
	s_add_i32 s54, s54, s2
	s_mov_b32 m0, s54
	ds_read_b128 v[164:167], v220 offset:16384
	ds_read_b128 v[192:195], v220 offset:17408
	ds_read_b128 v[196:199], v220 offset:18432
	ds_read_b128 v[200:203], v220 offset:19456
	ds_read_b128 v[222:225], v220 offset:20480
	ds_read_b128 v[226:229], v220 offset:21504
	ds_read_b128 v[230:233], v220 offset:22528
	ds_read_b128 v[234:237], v220 offset:23552
	global_load_lds_dwordx4 v184, s[26:27]
	s_add_i32 m0, s54, 0x2000
	s_add_u32 vcc_lo, s26, 0x40000
	v_lshl_add_u64 v[240:241], s[26:27], 0, v[180:181]
	s_addc_u32 vcc_hi, s27, 0
	s_add_i32 s54, s55, s2
	global_load_lds_dwordx4 v180, s[26:27]
	s_mov_b32 m0, s54
	v_lshl_add_u64 v[242:243], s[28:29], 0, v[186:187]
	global_load_lds_dwordx4 v184, vcc
	s_add_i32 m0, s54, 0x2000
	v_lshl_add_u64 v[244:245], s[28:29], 0, v[182:183]
	global_load_lds_dwordx4 v180, vcc
	s_mov_b32 m0, s37
	s_nop 0
	global_load_lds_dwordx4 v186, s[28:29]
	s_mov_b32 m0, s38
	s_nop 0
	global_load_lds_dwordx4 v182, s[28:29]
	s_waitcnt vmcnt(8)
	s_waitcnt lgkmcnt(0)
	s_barrier
	v_mfma_f32_16x16x32_bf16 v[72:75], v[52:55], v[164:167], v[72:75]
	v_mfma_f32_16x16x32_bf16 v[68:71], v[92:95], v[164:167], v[68:71]
	v_mfma_f32_16x16x32_bf16 v[48:51], v[52:55], v[196:199], v[48:51]
	v_mfma_f32_16x16x32_bf16 v[44:47], v[92:95], v[196:199], v[44:47]
	v_mfma_f32_16x16x32_bf16 v[32:35], v[52:55], v[222:225], v[32:35]
	v_mfma_f32_16x16x32_bf16 v[28:31], v[92:95], v[222:225], v[28:31]
	v_mfma_f32_16x16x32_bf16 v[16:19], v[52:55], v[230:233], v[16:19]
	v_mfma_f32_16x16x32_bf16 v[12:15], v[92:95], v[230:233], v[12:15]
	v_mfma_f32_16x16x32_bf16 v[72:75], v[56:59], v[192:195], v[72:75]
	v_mfma_f32_16x16x32_bf16 v[68:71], v[96:99], v[192:195], v[68:71]
	v_mfma_f32_16x16x32_bf16 v[48:51], v[56:59], v[200:203], v[48:51]
	v_mfma_f32_16x16x32_bf16 v[44:47], v[96:99], v[200:203], v[44:47]
	v_mfma_f32_16x16x32_bf16 v[32:35], v[56:59], v[226:229], v[32:35]
	v_mfma_f32_16x16x32_bf16 v[28:31], v[96:99], v[226:229], v[28:31]
	v_mfma_f32_16x16x32_bf16 v[16:19], v[56:59], v[234:237], v[16:19]
	v_mfma_f32_16x16x32_bf16 v[12:15], v[96:99], v[234:237], v[12:15]
	v_mfma_f32_16x16x32_bf16 v[40:43], v[124:127], v[196:199], v[40:43]
	v_mfma_f32_16x16x32_bf16 v[36:39], v[148:151], v[196:199], v[36:39]
	v_mfma_f32_16x16x32_bf16 v[24:27], v[124:127], v[222:225], v[24:27]
	v_mfma_f32_16x16x32_bf16 v[20:23], v[148:151], v[222:225], v[20:23]
	v_mfma_f32_16x16x32_bf16 v[8:11], v[124:127], v[230:233], v[8:11]
	v_mfma_f32_16x16x32_bf16 v[2:5], v[148:151], v[230:233], v[4:7]
	v_mfma_f32_16x16x32_bf16 v[52:55], v[124:127], v[164:167], v[64:67]
	v_mfma_f32_16x16x32_bf16 v[56:59], v[148:151], v[164:167], v[60:63]
	v_mfma_f32_16x16x32_bf16 v[40:43], v[128:131], v[200:203], v[40:43]
	v_mfma_f32_16x16x32_bf16 v[36:39], v[152:155], v[200:203], v[36:39]
	v_mfma_f32_16x16x32_bf16 v[24:27], v[128:131], v[226:229], v[24:27]
	v_mfma_f32_16x16x32_bf16 v[20:23], v[152:155], v[226:229], v[20:23]
	v_mfma_f32_16x16x32_bf16 v[8:11], v[128:131], v[234:237], v[8:11]
	v_mfma_f32_16x16x32_bf16 v[2:5], v[152:155], v[234:237], v[2:5]
	v_mfma_f32_16x16x32_bf16 v[52:55], v[128:131], v[192:195], v[52:55]
	v_mfma_f32_16x16x32_bf16 v[56:59], v[152:155], v[192:195], v[56:59]
	s_barrier
; #define PG8_STAGE(bufoff, gbase, voff) do { _Pragma("unroll") for (int _i = 0; _i < 2; ++_i) \
;         __builtin_amdgcn_global_load_lds((const unsigned*)((const char*)(gbase) + (voff)[_i]), (PG8_LAS unsigned*)(lds + (bufoff) + ldsw + _i * 8192), 16, 0, 0); } while (0)
; #define PG8_LDA(dst, b, h) do { _Pragma("unroll") for (int m = 0; m < 4; ++m) _Pragma("unroll") for (int k = 0; k < 2; ++k) dst[m][k] = *(const PG8_LAS bf16x8*)(lds + PG8_SA(b, h) + aoff + m * 2048 + k * 1024); } while (0)
; #define PG8_LDB(dst, b, h) do { _Pragma("unroll") for (int n = 0; n < 2; ++n) _Pragma("unroll") for (int k = 0; k < 2; ++k) dst[n][k] = *(const PG8_LAS bf16x8*)(lds + PG8_SB(b, h) + boff + n * 2048 + k * 1024); } while (0)
; #define PG8_MMA(ai, bj, At, Bt) do { __builtin_amdgcn_s_setprio(1); _Pragma("unroll") for (int m = 0; m < 4; ++m) _Pragma("unroll") for (int n = 0; n < 2; ++n) _Pragma("unroll") for (int k = 0; k < 2; ++k) \
;         acc[ai][bj][m][n] = __builtin_amdgcn_mfma_f32_16x16x32_bf16(Bt[n][k], At[m][k], acc[ai][bj][m][n], 0, 0, 0); __builtin_amdgcn_s_setprio(0); } while (0)
; #define PG8_WAIT_V(n) asm volatile("s_waitcnt vmcnt(" #n ")" ::: "memory")
; #define PG8_WAIT_L(n) asm volatile("s_waitcnt lgkmcnt(" #n ")" ::: "memory")
; #define PG8_BAR __builtin_amdgcn_s_barrier()
; #define PG8_SCHED __builtin_amdgcn_sched_barrier(0)
; template <class Epi, class Sched, bool ALIGN_EPI = false, bool SP2 = false>
; __device__ __forceinline__ void gemm_phase(PG8_LAS unsigned char* lds, const Gemm g, const Sched& S, const Epi& E) {
;     ...
;             PG8_LDB(B0, 1, 0); PG8_LDB(B1, 1, 1); PG8_SCHED; PG8_LDA(At, 1, 0); PG8_STAGE(PG8_SA(0, 1), a2 + hstep, voffA);
;             PG8_WAIT_V(8); PG8_WAIT_L(0); PG8_BAR; PG8_MMA(0, 0, At, B0); PG8_MMA(0, 1, At, B1); PG8_BAR; PG8_SCHED;
;             PG8_LDA(At, 1, 1); PG8_STAGE(PG8_SB(1, 0), b3, voffB); PG8_STAGE(PG8_SB(1, 1), b3 + hstep, voffB); PG8_STAGE(PG8_SA(1, 0), a3, voffA);
;             PG8_WAIT_V(8); PG8_WAIT_L(0); PG8_BAR; PG8_MMA(1, 0, At, B0); PG8_MMA(1, 1, At, B1); PG8_BAR; PG8_SCHED;
	s_add_i32 s54, 0, 0x18000
	s_add_i32 s55, 0, 0x1c000
	ds_read_b128 v[60:63], v218 offset:32768
	ds_read_b128 v[64:67], v218 offset:33792
	ds_read_b128 v[92:95], v218 offset:34816
	ds_read_b128 v[96:99], v218 offset:35840
	ds_read_b128 v[124:127], v218 offset:49152
	ds_read_b128 v[128:131], v218 offset:50176
	ds_read_b128 v[148:151], v218 offset:51200
	ds_read_b128 v[152:155], v218 offset:52224
	s_add_u32 s28, s28, 0x40000
	s_addc_u32 s29, s29, 0
	s_mov_b32 m0, s39
	ds_read_b128 v[164:167], v220 offset:32768
	ds_read_b128 v[192:195], v220 offset:33792
	ds_read_b128 v[196:199], v220 offset:34816
	ds_read_b128 v[200:203], v220 offset:35840
	ds_read_b128 v[222:225], v220 offset:36864
	ds_read_b128 v[226:229], v220 offset:37888
	ds_read_b128 v[230:233], v220 offset:38912
	ds_read_b128 v[234:237], v220 offset:39936
	global_load_lds_dwordx4 v186, s[28:29]
	s_mov_b32 m0, s44
	s_nop 0
	global_load_lds_dwordx4 v182, s[28:29]
	s_waitcnt vmcnt(8)
	s_waitcnt lgkmcnt(0)
	s_barrier
	v_mfma_f32_16x16x32_bf16 v[88:91], v[60:63], v[164:167], v[88:91]
	v_mfma_f32_16x16x32_bf16 v[84:87], v[92:95], v[164:167], v[84:87]
	v_mfma_f32_16x16x32_bf16 v[120:123], v[60:63], v[196:199], v[120:123]
	v_mfma_f32_16x16x32_bf16 v[108:111], v[92:95], v[196:199], v[108:111]
	v_mfma_f32_16x16x32_bf16 v[136:139], v[60:63], v[222:225], v[136:139]
	v_mfma_f32_16x16x32_bf16 v[132:135], v[92:95], v[222:225], v[132:135]
	v_mfma_f32_16x16x32_bf16 v[104:107], v[60:63], v[230:233], v[104:107]
	v_mfma_f32_16x16x32_bf16 v[100:103], v[92:95], v[230:233], v[100:103]
	v_mfma_f32_16x16x32_bf16 v[88:91], v[64:67], v[192:195], v[88:91]
	v_mfma_f32_16x16x32_bf16 v[84:87], v[96:99], v[192:195], v[84:87]
	v_mfma_f32_16x16x32_bf16 v[120:123], v[64:67], v[200:203], v[120:123]
	v_mfma_f32_16x16x32_bf16 v[108:111], v[96:99], v[200:203], v[108:111]
	v_mfma_f32_16x16x32_bf16 v[136:139], v[64:67], v[226:229], v[136:139]
	v_mfma_f32_16x16x32_bf16 v[132:135], v[96:99], v[226:229], v[132:135]
	v_mfma_f32_16x16x32_bf16 v[104:107], v[64:67], v[234:237], v[104:107]
	v_mfma_f32_16x16x32_bf16 v[100:103], v[96:99], v[234:237], v[100:103]
	v_mfma_f32_16x16x32_bf16 v[160:163], v[124:127], v[164:167], v[160:163]
	v_mfma_f32_16x16x32_bf16 v[156:159], v[148:151], v[164:167], v[156:159]
	v_mfma_f32_16x16x32_bf16 v[144:147], v[124:127], v[196:199], v[144:147]
	v_mfma_f32_16x16x32_bf16 v[140:143], v[148:151], v[196:199], v[140:143]
	v_mfma_f32_16x16x32_bf16 v[116:119], v[124:127], v[222:225], v[116:119]
	v_mfma_f32_16x16x32_bf16 v[112:115], v[148:151], v[222:225], v[112:115]
	v_mfma_f32_16x16x32_bf16 v[80:83], v[124:127], v[230:233], v[80:83]
	v_mfma_f32_16x16x32_bf16 v[76:79], v[148:151], v[230:233], v[76:79]
	v_mfma_f32_16x16x32_bf16 v[160:163], v[128:131], v[192:195], v[160:163]
	v_mfma_f32_16x16x32_bf16 v[156:159], v[152:155], v[192:195], v[156:159]
	v_mfma_f32_16x16x32_bf16 v[144:147], v[128:131], v[200:203], v[144:147]
	v_mfma_f32_16x16x32_bf16 v[140:143], v[152:155], v[200:203], v[140:143]
	v_mfma_f32_16x16x32_bf16 v[116:119], v[128:131], v[226:229], v[116:119]
	v_mfma_f32_16x16x32_bf16 v[112:115], v[152:155], v[226:229], v[112:115]
	v_mfma_f32_16x16x32_bf16 v[80:83], v[128:131], v[234:237], v[80:83]
	v_mfma_f32_16x16x32_bf16 v[76:79], v[152:155], v[234:237], v[76:79]
	s_barrier
	s_add_i32 s28, s54, s2
	s_add_i32 m0, s28, 0xffffff80
	ds_read_b128 v[164:167], v220 offset:49152
	ds_read_b128 v[192:195], v220 offset:50176
	ds_read_b128 v[196:199], v220 offset:51200
	ds_read_b128 v[200:203], v220 offset:52224
	ds_read_b128 v[222:225], v220 offset:53248
	ds_read_b128 v[226:229], v220 offset:54272
	ds_read_b128 v[230:233], v220 offset:55296
	ds_read_b128 v[234:237], v220 offset:56320
	global_load_lds_dwordx4 v184, s[26:27] offset:128
	s_add_i32 m0, s28, 0x2000
	s_add_u32 s26, s26, 0x40080
	v_lshl_add_u64 v[6:7], v[240:241], 0, s[34:35]
	s_addc_u32 s27, s27, 0
	s_add_i32 s28, s55, s2
	global_load_lds_dwordx4 v[6:7], off
	s_mov_b32 m0, s28
	s_nop 0
	global_load_lds_dwordx4 v184, s[26:27]
	s_add_i32 m0, s28, 0x2000
	s_nop 0
	global_load_lds_dwordx4 v180, s[26:27]
	v_lshl_add_u64 v[6:7], v[242:243], 0, s[34:35]
	s_mov_b32 m0, s47
	s_nop 0
	global_load_lds_dwordx4 v[6:7], off
	v_lshl_add_u64 v[6:7], v[244:245], 0, s[34:35]
	s_mov_b32 m0, s48
	s_nop 0
	global_load_lds_dwordx4 v[6:7], off
	s_waitcnt vmcnt(8)
	s_waitcnt lgkmcnt(0)
	s_barrier
	v_mfma_f32_16x16x32_bf16 v[72:75], v[60:63], v[164:167], v[72:75]
	v_mfma_f32_16x16x32_bf16 v[68:71], v[92:95], v[164:167], v[68:71]
	v_mfma_f32_16x16x32_bf16 v[48:51], v[60:63], v[196:199], v[48:51]
	v_mfma_f32_16x16x32_bf16 v[44:47], v[92:95], v[196:199], v[44:47]
	v_mfma_f32_16x16x32_bf16 v[32:35], v[60:63], v[222:225], v[32:35]
	v_mfma_f32_16x16x32_bf16 v[28:31], v[92:95], v[222:225], v[28:31]
	v_mfma_f32_16x16x32_bf16 v[16:19], v[60:63], v[230:233], v[16:19]
	v_mfma_f32_16x16x32_bf16 v[12:15], v[92:95], v[230:233], v[12:15]
	v_mfma_f32_16x16x32_bf16 v[72:75], v[64:67], v[192:195], v[72:75]
	v_mfma_f32_16x16x32_bf16 v[68:71], v[96:99], v[192:195], v[68:71]
	v_mfma_f32_16x16x32_bf16 v[48:51], v[64:67], v[200:203], v[48:51]
	v_mfma_f32_16x16x32_bf16 v[44:47], v[96:99], v[200:203], v[44:47]
	v_mfma_f32_16x16x32_bf16 v[32:35], v[64:67], v[226:229], v[32:35]
	v_mfma_f32_16x16x32_bf16 v[28:31], v[96:99], v[226:229], v[28:31]
	v_mfma_f32_16x16x32_bf16 v[16:19], v[64:67], v[234:237], v[16:19]
	v_mfma_f32_16x16x32_bf16 v[12:15], v[96:99], v[234:237], v[12:15]
	v_mfma_f32_16x16x32_bf16 v[52:55], v[124:127], v[164:167], v[52:55]
	v_mfma_f32_16x16x32_bf16 v[64:67], v[128:131], v[192:195], v[52:55]
	v_mfma_f32_16x16x32_bf16 v[52:55], v[148:151], v[164:167], v[56:59]
	v_mfma_f32_16x16x32_bf16 v[40:43], v[124:127], v[196:199], v[40:43]
	v_mfma_f32_16x16x32_bf16 v[36:39], v[148:151], v[196:199], v[36:39]
	v_mfma_f32_16x16x32_bf16 v[24:27], v[124:127], v[222:225], v[24:27]
	v_mfma_f32_16x16x32_bf16 v[20:23], v[148:151], v[222:225], v[20:23]
	v_mfma_f32_16x16x32_bf16 v[6:9], v[124:127], v[230:233], v[8:11]
	v_mfma_f32_16x16x32_bf16 v[2:5], v[148:151], v[230:233], v[2:5]
	v_mfma_f32_16x16x32_bf16 v[60:63], v[152:155], v[192:195], v[52:55]
	v_mfma_f32_16x16x32_bf16 v[40:43], v[128:131], v[200:203], v[40:43]
	v_mfma_f32_16x16x32_bf16 v[36:39], v[152:155], v[200:203], v[36:39]
	v_mfma_f32_16x16x32_bf16 v[24:27], v[128:131], v[226:229], v[24:27]
	v_mfma_f32_16x16x32_bf16 v[20:23], v[152:155], v[226:229], v[20:23]
	v_mfma_f32_16x16x32_bf16 v[8:11], v[128:131], v[234:237], v[6:9]
	v_mfma_f32_16x16x32_bf16 v[4:7], v[152:155], v[234:237], v[2:5]
	s_barrier
	s_add_i32 s78, s78, 2
	s_add_u32 s16, s16, 0x100
	s_addc_u32 s17, s17, 0
	s_add_u32 s73, s73, 0x100
	s_addc_u32 s77, s77, 0
	s_cmp_gt_u32 s78, 13
	s_cbranch_scc0 .LBB0_429
	s_and_b64 vcc, exec, s[6:7]
	s_cbranch_vccz .LBB0_432
	s_barrier

; #define PG8_WAIT_V(n) asm volatile("s_waitcnt vmcnt(" #n ")" ::: "memory")
; #define PG8_BAR __builtin_amdgcn_s_barrier()
; template <class Epi, class Sched, bool ALIGN_EPI = false, bool SP2 = false>
; __device__ __forceinline__ void gemm_phase(PG8_LAS unsigned char* lds, const Gemm g, const Sched& S, const Epi& E) {
;     ...
;     for (int i = 0; i < 2; ++i) { int R, C; stage_rc(tid * 16 + i * 8192, R, C); const int Rb = Epi::PERM ? ((R & ~31) + perm32(R & 31)) : R;
;         voffA[i] = (unsigned)(R * K + C) * 2u; voffB[i] = (unsigned)(Rb * K + C) * 2u; }
;     const size_t kstep = (size_t)(BK * 2);
;     const size_t hstep = (size_t)HALF * K * 2;
;     const size_t tstep = 2 * hstep;
;     const unsigned ldsw = (unsigned)wid * 1024u;
;     const int aoff = lds_byte(wr * 64 + fr, fq * 8), boff = lds_byte(wc * 32 + fr, fq * 8);
;     ...
;     Unit cur, nxt; int ui = 0;
;     if (!S.next(0, cur)) return;
;     f32x4 acc[2][2][4][2];
; #pragma unroll
;     for (int a = 0; a < 2; ++a)
; #pragma unroll
;         for (int b = 0; b < 2; ++b)
; #pragma unroll
;             for (int m = 0; m < 4; ++m)
; #pragma unroll
;                 for (int n = 0; n < 2; ++n) acc[a][b][m][n] = (f32x4){0.f, 0.f, 0.f, 0.f};
;     bf16x8 At[4][2], B0[2][2], B1[2][2];
;     const char* cA = (const char*)(cur.part ? g.A1 : g.A) + (size_t)cur.pm * tstep; const char* cB = (const char*)(cur.part ? g.Bt1 : g.Bt) + (size_t)cur.pn * tstep;
;     S.a_ready(cur);
;     if constexpr (SP2) {
;         PG8_STAGE(PG8_SB(0, 0), cB, voffB); PG8_STAGE(PG8_SB(0, 1), cB + hstep, voffB); PG8_STAGE(PG8_SA(0, 0), cA, voffA); PG8_STAGE(PG8_SA(0, 1), cA + hstep, voffA);
;         E.after_first_stage(tid);
;         if (wr == 1) PG8_BAR;
;         PG8_WAIT_V(2); PG8_BAR;
;         PG8_STAGE(PG8_SB(1, 0), cB + kstep, voffB); PG8_STAGE(PG8_SA(1, 0), cA + kstep, voffA); PG8_STAGE(PG8_SB(1, 1), cB + hstep + kstep, voffB);
;         PG8_WAIT_V(6); PG8_BAR;
;     } else {
;         PG8_STAGE(PG8_SB(0, 0), cB, voffB); PG8_STAGE(PG8_SA(0, 0), cA, voffA); PG8_STAGE(PG8_SB(0, 1), cB + hstep, voffB); PG8_STAGE(PG8_SA(0, 1), cA + hstep, voffA);
;         if (wr == 1) PG8_BAR;
;         PG8_WAIT_V(4); PG8_BAR;
;         PG8_STAGE(PG8_SB(1, 0), cB + kstep, voffB); PG8_STAGE(PG8_SA(1, 0), cA + kstep, voffA); PG8_STAGE(PG8_SB(1, 1), cB + hstep + kstep, voffB);
;         PG8_WAIT_V(6); PG8_BAR;
;     }
.LBB0_543:
	s_lshl_b32 s4, s64, 17
	s_lshl_b64 s[18:19], s[4:5], 2
	v_readlane_b32 s4, v250, 40
	s_add_u32 s4, s4, s18
	v_readlane_b32 s17, v250, 41
	s_addc_u32 s17, s17, s19
	v_bfe_u32 v13, v12, 4, 2
	v_readlane_b32 s24, v248, 26
	s_add_u32 s4, s4, 0x40000
	v_and_b32_e32 v18, 15, v12
	v_lshlrev_b32_e32 v20, 4, v13
	v_lshlrev_b32_e32 v12, 2, v12
	v_mov_b32_e32 v159, v1
	v_readlane_b32 s25, v248, 27
	s_addc_u32 s52, s17, 0
	s_and_b32 s17, s7, 3
	v_lshl_or_b32 v190, s6, 6, v18
	v_lshl_or_b32 v21, v18, 6, v20
	s_lshl_b32 s6, s6, 13
	v_and_b32_e32 v12, 32, v12
	s_add_i32 m0, s48, 0x18000
	v_lshl_add_u64 v[2:3], v[2:3], 0, s[34:35]
	v_lshl_add_u64 v[14:15], s[24:25], 0, v[158:159]
	v_mov_b32_e32 v157, v1
	v_bitop3_b32 v22, v21, s6, v12 bitop3:0xde
	s_lshl_b32 s6, s17, 12
	s_waitcnt vmcnt(2)
	s_barrier
	global_load_lds_dwordx4 v[2:3], off
	v_lshl_add_u64 v[2:3], v[4:5], 0, s[34:35]
	s_add_i32 m0, s48, 0x1a000
	s_add_i32 s53, s48, 0x8000
	s_add_i32 s73, s48, 0xa000
	v_lshl_add_u64 v[16:17], s[24:25], 0, v[156:157]
	v_bitop3_b32 v191, v21, s6, v12 bitop3:0xde
	v_add_u32_e32 v191, 0x10000, v191
	global_load_lds_dwordx4 v[2:3], off
	v_lshl_add_u64 v[2:3], v[14:15], 0, s[34:35]
	s_mov_b32 m0, s53
	s_add_u32 s6, s26, 0x80080
	global_load_lds_dwordx4 v[2:3], off
	v_lshl_add_u64 v[2:3], v[16:17], 0, s[34:35]
	s_mov_b32 m0, s73
	s_addc_u32 s7, s27, 0
	global_load_lds_dwordx4 v[2:3], off
	s_add_i32 m0, s48, 0x1c000
	v_lshl_add_u64 v[2:3], s[6:7], 0, v[0:1]
	global_load_lds_dwordx4 v[2:3], off
	v_lshl_add_u64 v[2:3], s[6:7], 0, v[154:155]
	s_add_i32 m0, s48, 0x1e000
	s_cmpk_lt_u32 s16, 0x100
	global_load_lds_dwordx4 v[2:3], off
	s_cselect_b64 s[6:7], -1, 0
	s_and_b32 s16, s16, 0xffffff00
	s_lshl_b32 s18, s17, 6
	s_or_b32 s16, s18, s16
	v_lshlrev_b32_e32 v3, 15, v10
	v_or3_b32 v160, s16, v20, v18
	s_movk_i32 s16, 0x100
	v_and_b32_e32 v3, 0xffff0000, v3
	v_cmp_gt_i32_e64 s[42:43], s16, v160
	s_lshl_b32 s16, s17, 2
	v_lshl_add_u32 v3, v9, 12, v3
	v_and_b32_e32 v4, 1, v10
	s_add_i32 s16, s16, 0
	v_lshl_or_b32 v3, v4, 6, v3
	s_add_i32 s16, s16, 0x22c00
	v_lshl_add_u32 v162, v11, 1, v3
	v_lshlrev_b32_e32 v3, 15, v6
	v_lshlrev_b32_e32 v19, 3, v13
	v_lshl_add_u32 v193, v190, 4, s16
	v_and_b32_e32 v3, 0xffff0000, v3
	v_readlane_b32 s16, v248, 11
	s_waitcnt vmcnt(6)
	v_lshl_or_b32 v192, s17, 5, v19
	v_lshlrev_b32_e32 v2, 4, v160
	v_lshl_add_u32 v3, v7, 12, v3
	v_and_b32_e32 v4, 1, v6
	s_mov_b32 s18, s16
	v_readlane_b32 s16, v248, 30
	v_lshl_or_b32 v3, v4, 6, v3
	v_add_u32_e32 v2, 0, v2
	v_readlane_b32 s17, v248, 31
	s_mov_b32 s77, 0
	v_cmp_eq_u32_e64 s[40:41], 0, v13
	v_ashrrev_i32_e32 v161, 31, v160
	v_mov_b32_e32 v163, v1
	v_lshl_add_u32 v164, v8, 1, v3
	v_mov_b32_e32 v165, v1
	v_add_u32_e32 v194, 0, v22
	v_add_u32_e32 v195, 0x22c00, v2
	s_mov_b32 s19, s16
	s_mov_b64 s[16:17], s[24:25]
	s_barrier
	s_branch .LBB0_546

; #define PG8_STAGE(bufoff, gbase, voff) do { _Pragma("unroll") for (int _i = 0; _i < 2; ++_i) \
;         __builtin_amdgcn_global_load_lds((const unsigned*)((const char*)(gbase) + (voff)[_i]), (PG8_LAS unsigned*)(lds + (bufoff) + ldsw + _i * 8192), 16, 0, 0); } while (0)
; #define PG8_LDA(dst, b, h) do { _Pragma("unroll") for (int m = 0; m < 4; ++m) _Pragma("unroll") for (int k = 0; k < 2; ++k) dst[m][k] = *(const PG8_LAS bf16x8*)(lds + PG8_SA(b, h) + aoff + m * 2048 + k * 1024); } while (0)
; #define PG8_LDB(dst, b, h) do { _Pragma("unroll") for (int n = 0; n < 2; ++n) _Pragma("unroll") for (int k = 0; k < 2; ++k) dst[n][k] = *(const PG8_LAS bf16x8*)(lds + PG8_SB(b, h) + boff + n * 2048 + k * 1024); } while (0)
; #define PG8_MMA(ai, bj, At, Bt) do { __builtin_amdgcn_s_setprio(1); _Pragma("unroll") for (int m = 0; m < 4; ++m) _Pragma("unroll") for (int n = 0; n < 2; ++n) _Pragma("unroll") for (int k = 0; k < 2; ++k) \
;         acc[ai][bj][m][n] = __builtin_amdgcn_mfma_f32_16x16x32_bf16(Bt[n][k], At[m][k], acc[ai][bj][m][n], 0, 0, 0); __builtin_amdgcn_s_setprio(0); } while (0)
; #define PG8_WAIT_V(n) asm volatile("s_waitcnt vmcnt(" #n ")" ::: "memory")
; #define PG8_WAIT_L(n) asm volatile("s_waitcnt lgkmcnt(" #n ")" ::: "memory")
; template <class Epi, class Sched, bool ALIGN_EPI = false, bool SP2 = false>
; __device__ __forceinline__ void gemm_phase(PG8_LAS unsigned char* lds, const Gemm g, const Sched& S, const Epi& E) {
;     ...
;             const bool last = (t == nt - 2);
;             const char* a1 = cA + (size_t)(t + 1) * kstep;
;             const char* a2 = last ? nA : cA + (size_t)(t + 2) * kstep; const char* b2 = last ? nB : cB + (size_t)(t + 2) * kstep;
;             const char* a3 = a2 + kstep; const char* b3 = b2 + kstep;
;             if (last && has_next) S.a_ready(nxt);
;             if constexpr (SP2) {
;             PG8_LDB(B0, 0, 0); PG8_LDB(B1, 0, 1); PG8_SCHED; PG8_LDA(At, 0, 0); PG8_STAGE(PG8_SA(1, 1), a1 + hstep, voffA);
;             PG8_WAIT_V(8); PG8_WAIT_L(0); PG8_BAR; PG8_MMA(0, 0, At, B0); PG8_MMA(0, 1, At, B1); PG8_BAR; PG8_SCHED;
;             PG8_LDA(At, 0, 1); PG8_STAGE(PG8_SB(0, 0), b2, voffB); PG8_STAGE(PG8_SB(0, 1), b2 + hstep, voffB); PG8_STAGE(PG8_SA(0, 0), a2, voffA);
;             PG8_WAIT_V(8); PG8_WAIT_L(0); PG8_BAR; PG8_MMA(1, 0, At, B0); PG8_MMA(1, 1, At, B1); PG8_BAR; PG8_SCHED;
.LBB0_553:
	s_add_u32 s26, s16, 0xfff80080
	s_addc_u32 s27, s17, -1
	s_add_i32 s54, 0, 0x10000
	s_cmp_eq_u32 vcc_hi, 28
	s_cselect_b32 s29, s23, s27
	s_cselect_b32 s28, s38, s26
	s_cselect_b32 s27, s21, vcc_lo
	s_cselect_b32 s26, s39, s78
	s_add_i32 s80, 0, 0x14000
	ds_read_b128 v[114:117], v191
	ds_read_b128 v[118:121], v191 offset:1024
	ds_read_b128 v[122:125], v191 offset:2048
	ds_read_b128 v[134:137], v191 offset:3072
	ds_read_b128 v[146:149], v191 offset:16384
	ds_read_b128 v[150:153], v191 offset:17408
	ds_read_b128 v[180:183], v191 offset:18432
	ds_read_b128 v[184:187], v191 offset:19456
	s_add_i32 m0, s48, 0xc000
	ds_read_b128 v[196:199], v194
	ds_read_b128 v[200:203], v194 offset:1024
	ds_read_b128 v[218:221], v194 offset:2048
	ds_read_b128 v[222:225], v194 offset:3072
	ds_read_b128 v[226:229], v194 offset:4096
	ds_read_b128 v[230:233], v194 offset:5120
	ds_read_b128 v[234:237], v194 offset:6144
	ds_read_b128 v[238:241], v194 offset:7168
	global_load_lds_dwordx4 v162, s[16:17]
	s_add_i32 m0, s48, 0xe000
	s_nop 0
	global_load_lds_dwordx4 v164, s[16:17]
	s_waitcnt vmcnt(8)
	s_waitcnt lgkmcnt(0)
	s_barrier
	v_mfma_f32_16x16x32_bf16 v[142:145], v[114:117], v[196:199], v[142:145]
	v_mfma_f32_16x16x32_bf16 v[138:141], v[122:125], v[196:199], v[138:141]
	v_mfma_f32_16x16x32_bf16 v[110:113], v[114:117], v[218:221], v[110:113]
	v_mfma_f32_16x16x32_bf16 v[106:109], v[122:125], v[218:221], v[106:109]
	v_mfma_f32_16x16x32_bf16 v[94:97], v[114:117], v[226:229], v[94:97]
	v_mfma_f32_16x16x32_bf16 v[90:93], v[122:125], v[226:229], v[90:93]
	v_mfma_f32_16x16x32_bf16 v[78:81], v[114:117], v[234:237], v[78:81]
	v_mfma_f32_16x16x32_bf16 v[74:77], v[122:125], v[234:237], v[74:77]
	v_mfma_f32_16x16x32_bf16 v[142:145], v[118:121], v[200:203], v[142:145]
	v_mfma_f32_16x16x32_bf16 v[138:141], v[134:137], v[200:203], v[138:141]
	v_mfma_f32_16x16x32_bf16 v[110:113], v[118:121], v[222:225], v[110:113]
	v_mfma_f32_16x16x32_bf16 v[106:109], v[134:137], v[222:225], v[106:109]
	v_mfma_f32_16x16x32_bf16 v[94:97], v[118:121], v[230:233], v[94:97]
	v_mfma_f32_16x16x32_bf16 v[90:93], v[134:137], v[230:233], v[90:93]
	v_mfma_f32_16x16x32_bf16 v[78:81], v[118:121], v[238:241], v[78:81]
	v_mfma_f32_16x16x32_bf16 v[74:77], v[134:137], v[238:241], v[74:77]
	v_mfma_f32_16x16x32_bf16 v[130:133], v[146:149], v[196:199], v[130:133]
	v_mfma_f32_16x16x32_bf16 v[126:129], v[180:183], v[196:199], v[126:129]
	v_mfma_f32_16x16x32_bf16 v[102:105], v[146:149], v[218:221], v[102:105]
	v_mfma_f32_16x16x32_bf16 v[98:101], v[180:183], v[218:221], v[98:101]
	v_mfma_f32_16x16x32_bf16 v[86:89], v[146:149], v[226:229], v[86:89]
	v_mfma_f32_16x16x32_bf16 v[82:85], v[180:183], v[226:229], v[82:85]
	v_mfma_f32_16x16x32_bf16 v[70:73], v[146:149], v[234:237], v[70:73]
	v_mfma_f32_16x16x32_bf16 v[66:69], v[180:183], v[234:237], v[66:69]
	v_mfma_f32_16x16x32_bf16 v[130:133], v[150:153], v[200:203], v[130:133]
	v_mfma_f32_16x16x32_bf16 v[126:129], v[184:187], v[200:203], v[126:129]
	v_mfma_f32_16x16x32_bf16 v[102:105], v[150:153], v[222:225], v[102:105]
	v_mfma_f32_16x16x32_bf16 v[98:101], v[184:187], v[222:225], v[98:101]
	v_mfma_f32_16x16x32_bf16 v[86:89], v[150:153], v[230:233], v[86:89]
	v_mfma_f32_16x16x32_bf16 v[82:85], v[184:187], v[230:233], v[82:85]
	v_mfma_f32_16x16x32_bf16 v[70:73], v[150:153], v[238:241], v[70:73]
	v_mfma_f32_16x16x32_bf16 v[66:69], v[184:187], v[238:241], v[66:69]
	s_barrier
	s_add_i32 s54, s54, s2
	s_mov_b32 m0, s54
	ds_read_b128 v[196:199], v194 offset:16384
	ds_read_b128 v[200:203], v194 offset:17408
	ds_read_b128 v[218:221], v194 offset:18432
	ds_read_b128 v[222:225], v194 offset:19456
	ds_read_b128 v[226:229], v194 offset:20480
	ds_read_b128 v[230:233], v194 offset:21504
	ds_read_b128 v[234:237], v194 offset:22528
	ds_read_b128 v[238:241], v194 offset:23552
	global_load_lds_dwordx4 v0, s[26:27]
	s_add_i32 m0, s54, 0x2000
	s_add_u32 s54, s26, 0x80000
	v_lshl_add_u64 v[188:189], s[26:27], 0, v[154:155]
	s_addc_u32 s55, s27, 0
	s_add_i32 s80, s80, s2
	global_load_lds_dwordx4 v154, s[26:27]
	s_mov_b32 m0, s80
	v_lshl_add_u64 v[244:245], s[28:29], 0, v[156:157]
	global_load_lds_dwordx4 v0, s[54:55]
	s_add_i32 m0, s80, 0x2000
	s_nop 0
	global_load_lds_dwordx4 v154, s[54:55]
	v_lshl_add_u64 v[242:243], s[28:29], 0, v[158:159]
	s_mov_b32 m0, s48
	s_nop 0
	global_load_lds_dwordx4 v158, s[28:29]
	s_mov_b32 m0, s49
	s_nop 0
	global_load_lds_dwordx4 v156, s[28:29]
	s_waitcnt vmcnt(8)
	s_waitcnt lgkmcnt(0)
	s_barrier
	v_mfma_f32_16x16x32_bf16 v[62:65], v[114:117], v[196:199], v[62:65]
	v_mfma_f32_16x16x32_bf16 v[58:61], v[122:125], v[196:199], v[58:61]
	v_mfma_f32_16x16x32_bf16 v[46:49], v[114:117], v[218:221], v[46:49]
	v_mfma_f32_16x16x32_bf16 v[42:45], v[122:125], v[218:221], v[42:45]
	v_mfma_f32_16x16x32_bf16 v[30:33], v[114:117], v[226:229], v[30:33]
	v_mfma_f32_16x16x32_bf16 v[26:29], v[122:125], v[226:229], v[26:29]
	v_mfma_f32_16x16x32_bf16 v[14:17], v[114:117], v[234:237], v[14:17]
	v_mfma_f32_16x16x32_bf16 v[10:13], v[122:125], v[234:237], v[10:13]
	v_mfma_f32_16x16x32_bf16 v[62:65], v[118:121], v[200:203], v[62:65]
	v_mfma_f32_16x16x32_bf16 v[58:61], v[134:137], v[200:203], v[58:61]
	v_mfma_f32_16x16x32_bf16 v[46:49], v[118:121], v[222:225], v[46:49]
	v_mfma_f32_16x16x32_bf16 v[42:45], v[134:137], v[222:225], v[42:45]
	v_mfma_f32_16x16x32_bf16 v[30:33], v[118:121], v[230:233], v[30:33]
	v_mfma_f32_16x16x32_bf16 v[26:29], v[134:137], v[230:233], v[26:29]
	v_mfma_f32_16x16x32_bf16 v[14:17], v[118:121], v[238:241], v[14:17]
	v_mfma_f32_16x16x32_bf16 v[10:13], v[134:137], v[238:241], v[10:13]
	v_mfma_f32_16x16x32_bf16 v[54:57], v[146:149], v[196:199], v[54:57]
	v_mfma_f32_16x16x32_bf16 v[50:53], v[180:183], v[196:199], v[50:53]
	v_mfma_f32_16x16x32_bf16 v[38:41], v[146:149], v[218:221], v[38:41]
	v_mfma_f32_16x16x32_bf16 v[34:37], v[180:183], v[218:221], v[34:37]
	v_mfma_f32_16x16x32_bf16 v[22:25], v[146:149], v[226:229], v[22:25]
	v_mfma_f32_16x16x32_bf16 v[18:21], v[180:183], v[226:229], v[18:21]
	v_mfma_f32_16x16x32_bf16 v[6:9], v[146:149], v[234:237], v[6:9]
	v_mfma_f32_16x16x32_bf16 v[2:5], v[180:183], v[234:237], v[2:5]
	v_mfma_f32_16x16x32_bf16 v[54:57], v[150:153], v[200:203], v[54:57]
	v_mfma_f32_16x16x32_bf16 v[50:53], v[184:187], v[200:203], v[50:53]
	v_mfma_f32_16x16x32_bf16 v[38:41], v[150:153], v[222:225], v[38:41]
	v_mfma_f32_16x16x32_bf16 v[34:37], v[184:187], v[222:225], v[34:37]
	v_mfma_f32_16x16x32_bf16 v[22:25], v[150:153], v[230:233], v[22:25]
	v_mfma_f32_16x16x32_bf16 v[18:21], v[184:187], v[230:233], v[18:21]
	v_mfma_f32_16x16x32_bf16 v[6:9], v[150:153], v[238:241], v[6:9]
	v_mfma_f32_16x16x32_bf16 v[2:5], v[184:187], v[238:241], v[2:5]
	s_barrier
; #define PG8_STAGE(bufoff, gbase, voff) do { _Pragma("unroll") for (int _i = 0; _i < 2; ++_i) \
;         __builtin_amdgcn_global_load_lds((const unsigned*)((const char*)(gbase) + (voff)[_i]), (PG8_LAS unsigned*)(lds + (bufoff) + ldsw + _i * 8192), 16, 0, 0); } while (0)
; #define PG8_LDA(dst, b, h) do { _Pragma("unroll") for (int m = 0; m < 4; ++m) _Pragma("unroll") for (int k = 0; k < 2; ++k) dst[m][k] = *(const PG8_LAS bf16x8*)(lds + PG8_SA(b, h) + aoff + m * 2048 + k * 1024); } while (0)
; #define PG8_LDB(dst, b, h) do { _Pragma("unroll") for (int n = 0; n < 2; ++n) _Pragma("unroll") for (int k = 0; k < 2; ++k) dst[n][k] = *(const PG8_LAS bf16x8*)(lds + PG8_SB(b, h) + boff + n * 2048 + k * 1024); } while (0)
; #define PG8_MMA(ai, bj, At, Bt) do { __builtin_amdgcn_s_setprio(1); _Pragma("unroll") for (int m = 0; m < 4; ++m) _Pragma("unroll") for (int n = 0; n < 2; ++n) _Pragma("unroll") for (int k = 0; k < 2; ++k) \
;         acc[ai][bj][m][n] = __builtin_amdgcn_mfma_f32_16x16x32_bf16(Bt[n][k], At[m][k], acc[ai][bj][m][n], 0, 0, 0); __builtin_amdgcn_s_setprio(0); } while (0)
; #define PG8_WAIT_V(n) asm volatile("s_waitcnt vmcnt(" #n ")" ::: "memory")
; #define PG8_WAIT_L(n) asm volatile("s_waitcnt lgkmcnt(" #n ")" ::: "memory")
; #define PG8_BAR __builtin_amdgcn_s_barrier()
; #define PG8_SCHED __builtin_amdgcn_sched_barrier(0)
; template <class Epi, class Sched, bool ALIGN_EPI = false, bool SP2 = false>
; __device__ __forceinline__ void gemm_phase(PG8_LAS unsigned char* lds, const Gemm g, const Sched& S, const Epi& E) {
;     ...
;             PG8_LDB(B0, 1, 0); PG8_LDB(B1, 1, 1); PG8_SCHED; PG8_LDA(At, 1, 0); PG8_STAGE(PG8_SA(0, 1), a2 + hstep, voffA);
;             PG8_WAIT_V(8); PG8_WAIT_L(0); PG8_BAR; PG8_MMA(0, 0, At, B0); PG8_MMA(0, 1, At, B1); PG8_BAR; PG8_SCHED;
;             PG8_LDA(At, 1, 1); PG8_STAGE(PG8_SB(1, 0), b3, voffB); PG8_STAGE(PG8_SB(1, 1), b3 + hstep, voffB); PG8_STAGE(PG8_SA(1, 0), a3, voffA);
;             PG8_WAIT_V(8); PG8_WAIT_L(0); PG8_BAR; PG8_MMA(1, 0, At, B0); PG8_MMA(1, 1, At, B1); PG8_BAR; PG8_SCHED;
	s_add_i32 s54, 0, 0x18000
	s_add_i32 s55, 0, 0x1c000
	ds_read_b128 v[114:117], v191 offset:32768
	ds_read_b128 v[118:121], v191 offset:33792
	ds_read_b128 v[122:125], v191 offset:34816
	ds_read_b128 v[134:137], v191 offset:35840
	ds_read_b128 v[146:149], v191 offset:49152
	ds_read_b128 v[150:153], v191 offset:50176
	ds_read_b128 v[180:183], v191 offset:51200
	ds_read_b128 v[184:187], v191 offset:52224
	s_add_u32 s28, s28, 0x80000
	s_addc_u32 s29, s29, 0
	s_mov_b32 m0, s50
	ds_read_b128 v[196:199], v194 offset:32768
	ds_read_b128 v[200:203], v194 offset:33792
	ds_read_b128 v[218:221], v194 offset:34816
	ds_read_b128 v[222:225], v194 offset:35840
	ds_read_b128 v[226:229], v194 offset:36864
	ds_read_b128 v[230:233], v194 offset:37888
	ds_read_b128 v[234:237], v194 offset:38912
	ds_read_b128 v[238:241], v194 offset:39936
	global_load_lds_dwordx4 v158, s[28:29]
	s_mov_b32 m0, s51
	s_nop 0
	global_load_lds_dwordx4 v156, s[28:29]
	s_waitcnt vmcnt(8)
	s_waitcnt lgkmcnt(0)
	s_barrier
	v_mfma_f32_16x16x32_bf16 v[142:145], v[114:117], v[196:199], v[142:145]
	v_mfma_f32_16x16x32_bf16 v[138:141], v[122:125], v[196:199], v[138:141]
	v_mfma_f32_16x16x32_bf16 v[110:113], v[114:117], v[218:221], v[110:113]
	v_mfma_f32_16x16x32_bf16 v[106:109], v[122:125], v[218:221], v[106:109]
	v_mfma_f32_16x16x32_bf16 v[94:97], v[114:117], v[226:229], v[94:97]
	v_mfma_f32_16x16x32_bf16 v[90:93], v[122:125], v[226:229], v[90:93]
	v_mfma_f32_16x16x32_bf16 v[78:81], v[114:117], v[234:237], v[78:81]
	v_mfma_f32_16x16x32_bf16 v[74:77], v[122:125], v[234:237], v[74:77]
	v_mfma_f32_16x16x32_bf16 v[142:145], v[118:121], v[200:203], v[142:145]
	v_mfma_f32_16x16x32_bf16 v[138:141], v[134:137], v[200:203], v[138:141]
	v_mfma_f32_16x16x32_bf16 v[110:113], v[118:121], v[222:225], v[110:113]
	v_mfma_f32_16x16x32_bf16 v[106:109], v[134:137], v[222:225], v[106:109]
	v_mfma_f32_16x16x32_bf16 v[94:97], v[118:121], v[230:233], v[94:97]
	v_mfma_f32_16x16x32_bf16 v[90:93], v[134:137], v[230:233], v[90:93]
	v_mfma_f32_16x16x32_bf16 v[78:81], v[118:121], v[238:241], v[78:81]
	v_mfma_f32_16x16x32_bf16 v[74:77], v[134:137], v[238:241], v[74:77]
	v_mfma_f32_16x16x32_bf16 v[130:133], v[146:149], v[196:199], v[130:133]
	v_mfma_f32_16x16x32_bf16 v[126:129], v[180:183], v[196:199], v[126:129]
	v_mfma_f32_16x16x32_bf16 v[102:105], v[146:149], v[218:221], v[102:105]
	v_mfma_f32_16x16x32_bf16 v[98:101], v[180:183], v[218:221], v[98:101]
	v_mfma_f32_16x16x32_bf16 v[86:89], v[146:149], v[226:229], v[86:89]
	v_mfma_f32_16x16x32_bf16 v[82:85], v[180:183], v[226:229], v[82:85]
	v_mfma_f32_16x16x32_bf16 v[70:73], v[146:149], v[234:237], v[70:73]
	v_mfma_f32_16x16x32_bf16 v[66:69], v[180:183], v[234:237], v[66:69]
	v_mfma_f32_16x16x32_bf16 v[130:133], v[150:153], v[200:203], v[130:133]
	v_mfma_f32_16x16x32_bf16 v[126:129], v[184:187], v[200:203], v[126:129]
	v_mfma_f32_16x16x32_bf16 v[102:105], v[150:153], v[222:225], v[102:105]
	v_mfma_f32_16x16x32_bf16 v[98:101], v[184:187], v[222:225], v[98:101]
	v_mfma_f32_16x16x32_bf16 v[86:89], v[150:153], v[230:233], v[86:89]
	v_mfma_f32_16x16x32_bf16 v[82:85], v[184:187], v[230:233], v[82:85]
	v_mfma_f32_16x16x32_bf16 v[70:73], v[150:153], v[238:241], v[70:73]
	v_mfma_f32_16x16x32_bf16 v[66:69], v[184:187], v[238:241], v[66:69]
	s_barrier
	s_add_i32 s28, s54, s2
	s_add_i32 m0, s28, 0xffffff80
	ds_read_b128 v[196:199], v194 offset:49152
	ds_read_b128 v[200:203], v194 offset:50176
	ds_read_b128 v[218:221], v194 offset:51200
	ds_read_b128 v[222:225], v194 offset:52224
	ds_read_b128 v[226:229], v194 offset:53248
	ds_read_b128 v[230:233], v194 offset:54272
	ds_read_b128 v[234:237], v194 offset:55296
	ds_read_b128 v[238:241], v194 offset:56320
	global_load_lds_dwordx4 v0, s[26:27] offset:128
	s_add_i32 m0, s28, 0x2000
	s_add_u32 s26, s26, 0x80080
	v_lshl_add_u64 v[166:167], v[188:189], 0, s[34:35]
	s_addc_u32 s27, s27, 0
	s_add_i32 s28, s55, s2
	global_load_lds_dwordx4 v[166:167], off
	s_mov_b32 m0, s28
	s_nop 0
	global_load_lds_dwordx4 v0, s[26:27]
	s_add_i32 m0, s28, 0x2000
	s_nop 0
	global_load_lds_dwordx4 v154, s[26:27]
	v_lshl_add_u64 v[166:167], v[242:243], 0, s[34:35]
	s_mov_b32 m0, s53
	s_nop 0
	global_load_lds_dwordx4 v[166:167], off
	v_lshl_add_u64 v[166:167], v[244:245], 0, s[34:35]
	s_mov_b32 m0, s73
	s_nop 0
	global_load_lds_dwordx4 v[166:167], off
	s_waitcnt vmcnt(8)
	s_waitcnt lgkmcnt(0)
	s_barrier
	v_mfma_f32_16x16x32_bf16 v[62:65], v[114:117], v[196:199], v[62:65]
	v_mfma_f32_16x16x32_bf16 v[58:61], v[122:125], v[196:199], v[58:61]
	v_mfma_f32_16x16x32_bf16 v[46:49], v[114:117], v[218:221], v[46:49]
	v_mfma_f32_16x16x32_bf16 v[42:45], v[122:125], v[218:221], v[42:45]
	v_mfma_f32_16x16x32_bf16 v[30:33], v[114:117], v[226:229], v[30:33]
	v_mfma_f32_16x16x32_bf16 v[26:29], v[122:125], v[226:229], v[26:29]
	v_mfma_f32_16x16x32_bf16 v[14:17], v[114:117], v[234:237], v[14:17]
	v_mfma_f32_16x16x32_bf16 v[10:13], v[122:125], v[234:237], v[10:13]
	v_mfma_f32_16x16x32_bf16 v[62:65], v[118:121], v[200:203], v[62:65]
	v_mfma_f32_16x16x32_bf16 v[58:61], v[134:137], v[200:203], v[58:61]
	v_mfma_f32_16x16x32_bf16 v[46:49], v[118:121], v[222:225], v[46:49]
	v_mfma_f32_16x16x32_bf16 v[42:45], v[134:137], v[222:225], v[42:45]
	v_mfma_f32_16x16x32_bf16 v[30:33], v[118:121], v[230:233], v[30:33]
	v_mfma_f32_16x16x32_bf16 v[26:29], v[134:137], v[230:233], v[26:29]
	v_mfma_f32_16x16x32_bf16 v[14:17], v[118:121], v[238:241], v[14:17]
	v_mfma_f32_16x16x32_bf16 v[10:13], v[134:137], v[238:241], v[10:13]
	v_mfma_f32_16x16x32_bf16 v[54:57], v[146:149], v[196:199], v[54:57]
	v_mfma_f32_16x16x32_bf16 v[50:53], v[180:183], v[196:199], v[50:53]
	v_mfma_f32_16x16x32_bf16 v[38:41], v[146:149], v[218:221], v[38:41]
	v_mfma_f32_16x16x32_bf16 v[34:37], v[180:183], v[218:221], v[34:37]
	v_mfma_f32_16x16x32_bf16 v[22:25], v[146:149], v[226:229], v[22:25]
	v_mfma_f32_16x16x32_bf16 v[18:21], v[180:183], v[226:229], v[18:21]
	v_mfma_f32_16x16x32_bf16 v[6:9], v[146:149], v[234:237], v[6:9]
	v_mfma_f32_16x16x32_bf16 v[2:5], v[180:183], v[234:237], v[2:5]
	v_mfma_f32_16x16x32_bf16 v[54:57], v[150:153], v[200:203], v[54:57]
	v_mfma_f32_16x16x32_bf16 v[50:53], v[184:187], v[200:203], v[50:53]
	v_mfma_f32_16x16x32_bf16 v[38:41], v[150:153], v[222:225], v[38:41]
	v_mfma_f32_16x16x32_bf16 v[34:37], v[184:187], v[222:225], v[34:37]
	v_mfma_f32_16x16x32_bf16 v[22:25], v[150:153], v[230:233], v[22:25]
	v_mfma_f32_16x16x32_bf16 v[18:21], v[184:187], v[230:233], v[18:21]
	v_mfma_f32_16x16x32_bf16 v[6:9], v[150:153], v[238:241], v[6:9]
	v_mfma_f32_16x16x32_bf16 v[2:5], v[184:187], v[238:241], v[2:5]
	s_barrier
	s_add_i32 vcc_hi, vcc_hi, 2
	s_add_u32 s16, s16, 0x100
	s_addc_u32 s17, s17, 0
	s_add_u32 s78, s78, 0x100
	s_addc_u32 vcc_lo, vcc_lo, 0
	s_cmp_gt_u32 vcc_hi, 29
	s_cbranch_scc0 .LBB0_553
	s_and_b64 vcc, exec, s[6:7]
	s_cbranch_vccz .LBB0_556
	s_barrier

; #define PG8_WAIT_V(n) asm volatile("s_waitcnt vmcnt(" #n ")" ::: "memory")
; #define PG8_BAR __builtin_amdgcn_s_barrier()
; template <class Epi, class Sched, bool ALIGN_EPI = false, bool SP2 = false>
; __device__ __forceinline__ void gemm_phase(PG8_LAS unsigned char* lds, const Gemm g, const Sched& S, const Epi& E) {
;     ...
;     for (int i = 0; i < 2; ++i) { int R, C; stage_rc(tid * 16 + i * 8192, R, C); const int Rb = Epi::PERM ? ((R & ~31) + perm32(R & 31)) : R;
;         voffA[i] = (unsigned)(R * K + C) * 2u; voffB[i] = (unsigned)(Rb * K + C) * 2u; }
;     const size_t kstep = (size_t)(BK * 2);
;     const size_t hstep = (size_t)HALF * K * 2;
;     const size_t tstep = 2 * hstep;
;     const unsigned ldsw = (unsigned)wid * 1024u;
;     const int aoff = lds_byte(wr * 64 + fr, fq * 8), boff = lds_byte(wc * 32 + fr, fq * 8);
;     ...
;     Unit cur, nxt; int ui = 0;
;     if (!S.next(0, cur)) return;
;     f32x4 acc[2][2][4][2];
; #pragma unroll
;     for (int a = 0; a < 2; ++a)
; #pragma unroll
;         for (int b = 0; b < 2; ++b)
; #pragma unroll
;             for (int m = 0; m < 4; ++m)
; #pragma unroll
;                 for (int n = 0; n < 2; ++n) acc[a][b][m][n] = (f32x4){0.f, 0.f, 0.f, 0.f};
;     bf16x8 At[4][2], B0[2][2], B1[2][2];
;     const char* cA = (const char*)(cur.part ? g.A1 : g.A) + (size_t)cur.pm * tstep; const char* cB = (const char*)(cur.part ? g.Bt1 : g.Bt) + (size_t)cur.pn * tstep;
;     S.a_ready(cur);
;     if constexpr (SP2) {
;         PG8_STAGE(PG8_SB(0, 0), cB, voffB); PG8_STAGE(PG8_SB(0, 1), cB + hstep, voffB); PG8_STAGE(PG8_SA(0, 0), cA, voffA); PG8_STAGE(PG8_SA(0, 1), cA + hstep, voffA);
;         E.after_first_stage(tid);
;         if (wr == 1) PG8_BAR;
;         PG8_WAIT_V(2); PG8_BAR;
;         PG8_STAGE(PG8_SB(1, 0), cB + kstep, voffB); PG8_STAGE(PG8_SA(1, 0), cA + kstep, voffA); PG8_STAGE(PG8_SB(1, 1), cB + hstep + kstep, voffB);
;         PG8_WAIT_V(6); PG8_BAR;
;     } else {
;         PG8_STAGE(PG8_SB(0, 0), cB, voffB); PG8_STAGE(PG8_SA(0, 0), cA, voffA); PG8_STAGE(PG8_SB(0, 1), cB + hstep, voffB); PG8_STAGE(PG8_SA(0, 1), cA + hstep, voffA);
;         if (wr == 1) PG8_BAR;
;         PG8_WAIT_V(4); PG8_BAR;
;         PG8_STAGE(PG8_SB(1, 0), cB + kstep, voffB); PG8_STAGE(PG8_SA(1, 0), cA + kstep, voffA); PG8_STAGE(PG8_SB(1, 1), cB + hstep + kstep, voffB);
;         PG8_WAIT_V(6); PG8_BAR;
;     }
.LBB0_653:
	v_and_b32_e32 v3, 15, v2
	v_bfe_u32 v18, v2, 4, 2
	v_lshlrev_b32_e32 v2, 4, v18
	v_lshlrev_b32_e32 v19, 2, v3
	v_lshl_or_b32 v158, s20, 6, v3
	v_lshl_or_b32 v2, v3, 6, v2
	s_lshl_b32 s4, s20, 13
	v_and_b32_e32 v3, 32, v19
	v_bitop3_b32 v20, v2, s4, v3 bitop3:0xde
	s_lshl_b32 s4, s19, 5
	s_and_b32 s21, s4, 0x60
	v_readlane_b32 s24, v248, 14
	s_lshl_b32 s4, s21, 7
	v_mov_b32_e32 v135, v1
	v_readlane_b32 s25, v248, 15
	v_bitop3_b32 v159, v2, s4, v3 bitop3:0xde
	v_add_u32_e32 v159, 0x10000, v159
	s_add_i32 m0, s45, 0x18000
	v_lshl_add_u64 v[2:3], v[4:5], 0, s[34:35]
	v_lshl_add_u64 v[14:15], s[24:25], 0, v[134:135]
	v_mov_b32_e32 v133, v1
	s_waitcnt vmcnt(2)
	s_barrier
	global_load_lds_dwordx4 v[2:3], off
	v_lshl_add_u64 v[2:3], v[6:7], 0, s[34:35]
	s_add_i32 m0, s45, 0x1a000
	s_add_i32 s4, s45, 0x8000
	s_add_i32 s49, s45, 0xa000
	v_lshl_add_u64 v[16:17], s[24:25], 0, v[132:133]
	global_load_lds_dwordx4 v[2:3], off
	v_lshl_add_u64 v[2:3], v[14:15], 0, s[34:35]
	s_mov_b32 m0, s4
	s_add_u32 s22, s26, 0x80080
	global_load_lds_dwordx4 v[2:3], off
	v_lshl_add_u64 v[2:3], v[16:17], 0, s[34:35]
	s_mov_b32 m0, s49
	s_addc_u32 s23, s27, 0
	global_load_lds_dwordx4 v[2:3], off
	s_add_i32 m0, s45, 0x1c000
	v_lshl_add_u64 v[2:3], s[22:23], 0, v[0:1]
	global_load_lds_dwordx4 v[2:3], off
	v_lshl_add_u64 v[2:3], s[22:23], 0, v[130:131]
	s_add_i32 m0, s45, 0x1e000
	s_cmpk_lt_u32 s18, 0x100
	global_load_lds_dwordx4 v[2:3], off
	v_lshlrev_b32_e32 v2, 16, v18
	v_mov_b32_e32 v3, v1
	v_lshl_add_u64 v[136:137], s[16:17], 0, v[2:3]
	v_lshlrev_b32_e32 v2, 15, v12
	v_and_b32_e32 v2, 0xffff0000, v2
	v_lshl_add_u32 v2, v11, 12, v2
	v_and_b32_e32 v3, 1, v12
	s_cselect_b64 s[18:19], -1, 0
	s_lshl_b32 s16, s20, 8
	v_lshl_or_b32 v2, v3, 6, v2
	s_add_i32 s16, s16, 0
	v_lshl_add_u32 v138, v13, 1, v2
	v_lshlrev_b32_e32 v2, 15, v8
	s_add_i32 s16, s16, 0x23c00
	v_and_b32_e32 v2, 0xffff0000, v2
	s_waitcnt vmcnt(6)
	v_add_u32_e32 v160, s16, v19
	v_lshl_add_u32 v2, v9, 12, v2
	v_and_b32_e32 v3, 1, v8
	v_readlane_b32 s16, v248, 12
	v_lshl_or_b32 v2, v3, 6, v2
	v_readlane_b32 s17, v248, 13
	v_lshl_or_b32 v161, v18, 3, s21
	v_mov_b32_e32 v139, v1
	v_lshl_add_u32 v140, v10, 1, v2
	v_mov_b32_e32 v141, v1
	s_mov_b32 s50, 0
	v_add_u32_e32 v162, 0, v20
	v_readlane_b32 s51, v248, 8
	s_mov_b32 s42, s16
	s_mov_b64 s[16:17], s[24:25]
	s_barrier
	s_branch .LBB0_656

; #define PG8_STAGE(bufoff, gbase, voff) do { _Pragma("unroll") for (int _i = 0; _i < 2; ++_i) \
;         __builtin_amdgcn_global_load_lds((const unsigned*)((const char*)(gbase) + (voff)[_i]), (PG8_LAS unsigned*)(lds + (bufoff) + ldsw + _i * 8192), 16, 0, 0); } while (0)
; #define PG8_LDA(dst, b, h) do { _Pragma("unroll") for (int m = 0; m < 4; ++m) _Pragma("unroll") for (int k = 0; k < 2; ++k) dst[m][k] = *(const PG8_LAS bf16x8*)(lds + PG8_SA(b, h) + aoff + m * 2048 + k * 1024); } while (0)
; #define PG8_LDB(dst, b, h) do { _Pragma("unroll") for (int n = 0; n < 2; ++n) _Pragma("unroll") for (int k = 0; k < 2; ++k) dst[n][k] = *(const PG8_LAS bf16x8*)(lds + PG8_SB(b, h) + boff + n * 2048 + k * 1024); } while (0)
; #define PG8_MMA(ai, bj, At, Bt) do { __builtin_amdgcn_s_setprio(1); _Pragma("unroll") for (int m = 0; m < 4; ++m) _Pragma("unroll") for (int n = 0; n < 2; ++n) _Pragma("unroll") for (int k = 0; k < 2; ++k) \
;         acc[ai][bj][m][n] = __builtin_amdgcn_mfma_f32_16x16x32_bf16(Bt[n][k], At[m][k], acc[ai][bj][m][n], 0, 0, 0); __builtin_amdgcn_s_setprio(0); } while (0)
; #define PG8_WAIT_V(n) asm volatile("s_waitcnt vmcnt(" #n ")" ::: "memory")
; #define PG8_WAIT_L(n) asm volatile("s_waitcnt lgkmcnt(" #n ")" ::: "memory")
; template <class Epi, class Sched, bool ALIGN_EPI = false, bool SP2 = false>
; __device__ __forceinline__ void gemm_phase(PG8_LAS unsigned char* lds, const Gemm g, const Sched& S, const Epi& E) {
;     ...
;             const bool last = (t == nt - 2);
;             const char* a1 = cA + (size_t)(t + 1) * kstep;
;             const char* a2 = last ? nA : cA + (size_t)(t + 2) * kstep; const char* b2 = last ? nB : cB + (size_t)(t + 2) * kstep;
;             const char* a3 = a2 + kstep; const char* b3 = b2 + kstep;
;             if (last && has_next) S.a_ready(nxt);
;             if constexpr (SP2) {
;             PG8_LDB(B0, 0, 0); PG8_LDB(B1, 0, 1); PG8_SCHED; PG8_LDA(At, 0, 0); PG8_STAGE(PG8_SA(1, 1), a1 + hstep, voffA);
;             PG8_WAIT_V(8); PG8_WAIT_L(0); PG8_BAR; PG8_MMA(0, 0, At, B0); PG8_MMA(0, 1, At, B1); PG8_BAR; PG8_SCHED;
;             PG8_LDA(At, 0, 1); PG8_STAGE(PG8_SB(0, 0), b2, voffB); PG8_STAGE(PG8_SB(0, 1), b2 + hstep, voffB); PG8_STAGE(PG8_SA(0, 0), a2, voffA);
;             PG8_WAIT_V(8); PG8_WAIT_L(0); PG8_BAR; PG8_MMA(1, 0, At, B0); PG8_MMA(1, 1, At, B1); PG8_BAR; PG8_SCHED;
.LBB0_659:
	s_add_u32 s26, s16, 0xfff80080
	s_addc_u32 s27, s17, -1
	s_add_i32 s54, 0, 0x10000
	s_cmp_eq_u32 s77, 28
	s_cselect_b32 s29, s23, s27
	s_cselect_b32 s28, s43, s26
	s_cselect_b32 s27, s21, s73
	s_cselect_b32 s26, s52, s53
	s_add_i32 s78, 0, 0x14000
	ds_read_b128 v[142:145], v159
	ds_read_b128 v[146:149], v159 offset:1024
	ds_read_b128 v[150:153], v159 offset:2048
	ds_read_b128 v[154:157], v159 offset:3072
	ds_read_b128 v[164:167], v159 offset:16384
	ds_read_b128 v[180:183], v159 offset:17408
	ds_read_b128 v[184:187], v159 offset:18432
	ds_read_b128 v[188:191], v159 offset:19456
	s_add_i32 m0, s45, 0xc000
	ds_read_b128 v[192:195], v162
	ds_read_b128 v[196:199], v162 offset:1024
	ds_read_b128 v[200:203], v162 offset:2048
	ds_read_b128 v[218:221], v162 offset:3072
	ds_read_b128 v[222:225], v162 offset:4096
	ds_read_b128 v[226:229], v162 offset:5120
	ds_read_b128 v[230:233], v162 offset:6144
	ds_read_b128 v[234:237], v162 offset:7168
	global_load_lds_dwordx4 v138, s[16:17]
	s_add_i32 m0, s45, 0xe000
	s_nop 0
	global_load_lds_dwordx4 v140, s[16:17]
	s_waitcnt vmcnt(8)
	s_waitcnt lgkmcnt(0)
	s_barrier
	v_mfma_f32_16x16x32_bf16 v[126:129], v[142:145], v[192:195], v[126:129]
	v_mfma_f32_16x16x32_bf16 v[118:121], v[150:153], v[192:195], v[118:121]
	v_mfma_f32_16x16x32_bf16 v[110:113], v[142:145], v[200:203], v[110:113]
	v_mfma_f32_16x16x32_bf16 v[102:105], v[150:153], v[200:203], v[102:105]
	v_mfma_f32_16x16x32_bf16 v[94:97], v[142:145], v[222:225], v[94:97]
	v_mfma_f32_16x16x32_bf16 v[86:89], v[150:153], v[222:225], v[86:89]
	v_mfma_f32_16x16x32_bf16 v[78:81], v[142:145], v[230:233], v[78:81]
	v_mfma_f32_16x16x32_bf16 v[70:73], v[150:153], v[230:233], v[70:73]
	v_mfma_f32_16x16x32_bf16 v[126:129], v[146:149], v[196:199], v[126:129]
	v_mfma_f32_16x16x32_bf16 v[118:121], v[154:157], v[196:199], v[118:121]
	v_mfma_f32_16x16x32_bf16 v[110:113], v[146:149], v[218:221], v[110:113]
	v_mfma_f32_16x16x32_bf16 v[102:105], v[154:157], v[218:221], v[102:105]
	v_mfma_f32_16x16x32_bf16 v[94:97], v[146:149], v[226:229], v[94:97]
	v_mfma_f32_16x16x32_bf16 v[86:89], v[154:157], v[226:229], v[86:89]
	v_mfma_f32_16x16x32_bf16 v[78:81], v[146:149], v[234:237], v[78:81]
	v_mfma_f32_16x16x32_bf16 v[70:73], v[154:157], v[234:237], v[70:73]
	v_mfma_f32_16x16x32_bf16 v[122:125], v[164:167], v[192:195], v[122:125]
	v_mfma_f32_16x16x32_bf16 v[114:117], v[184:187], v[192:195], v[114:117]
	v_mfma_f32_16x16x32_bf16 v[106:109], v[164:167], v[200:203], v[106:109]
	v_mfma_f32_16x16x32_bf16 v[98:101], v[184:187], v[200:203], v[98:101]
	v_mfma_f32_16x16x32_bf16 v[90:93], v[164:167], v[222:225], v[90:93]
	v_mfma_f32_16x16x32_bf16 v[82:85], v[184:187], v[222:225], v[82:85]
	v_mfma_f32_16x16x32_bf16 v[74:77], v[164:167], v[230:233], v[74:77]
	v_mfma_f32_16x16x32_bf16 v[66:69], v[184:187], v[230:233], v[66:69]
	v_mfma_f32_16x16x32_bf16 v[122:125], v[180:183], v[196:199], v[122:125]
	v_mfma_f32_16x16x32_bf16 v[114:117], v[188:191], v[196:199], v[114:117]
	v_mfma_f32_16x16x32_bf16 v[106:109], v[180:183], v[218:221], v[106:109]
	v_mfma_f32_16x16x32_bf16 v[98:101], v[188:191], v[218:221], v[98:101]
	v_mfma_f32_16x16x32_bf16 v[90:93], v[180:183], v[226:229], v[90:93]
	v_mfma_f32_16x16x32_bf16 v[82:85], v[188:191], v[226:229], v[82:85]
	v_mfma_f32_16x16x32_bf16 v[74:77], v[180:183], v[234:237], v[74:77]
	v_mfma_f32_16x16x32_bf16 v[66:69], v[188:191], v[234:237], v[66:69]
	s_barrier
	s_add_i32 s54, s54, s38
	s_mov_b32 m0, s54
	ds_read_b128 v[192:195], v162 offset:16384
	ds_read_b128 v[196:199], v162 offset:17408
	ds_read_b128 v[200:203], v162 offset:18432
	ds_read_b128 v[218:221], v162 offset:19456
	ds_read_b128 v[222:225], v162 offset:20480
	ds_read_b128 v[226:229], v162 offset:21504
	ds_read_b128 v[230:233], v162 offset:22528
	ds_read_b128 v[234:237], v162 offset:23552
	global_load_lds_dwordx4 v0, s[26:27]
	s_add_i32 m0, s54, 0x2000
	s_add_u32 s54, s26, 0x80000
	v_lshl_add_u64 v[240:241], s[26:27], 0, v[130:131]
	s_addc_u32 s55, s27, 0
	s_add_i32 s78, s78, s38
	global_load_lds_dwordx4 v130, s[26:27]
	s_mov_b32 m0, s78
	v_lshl_add_u64 v[244:245], s[28:29], 0, v[132:133]
	global_load_lds_dwordx4 v0, s[54:55]
	s_add_i32 m0, s78, 0x2000
	s_nop 0
	global_load_lds_dwordx4 v130, s[54:55]
	v_lshl_add_u64 v[242:243], s[28:29], 0, v[134:135]
	s_mov_b32 m0, s45
	s_nop 0
	global_load_lds_dwordx4 v134, s[28:29]
	s_mov_b32 m0, s46
	s_nop 0
	global_load_lds_dwordx4 v132, s[28:29]
	s_waitcnt vmcnt(8)
	s_waitcnt lgkmcnt(0)
	s_barrier
	v_mfma_f32_16x16x32_bf16 v[62:65], v[142:145], v[192:195], v[62:65]
	v_mfma_f32_16x16x32_bf16 v[54:57], v[150:153], v[192:195], v[54:57]
	v_mfma_f32_16x16x32_bf16 v[46:49], v[142:145], v[200:203], v[46:49]
	v_mfma_f32_16x16x32_bf16 v[38:41], v[150:153], v[200:203], v[38:41]
	v_mfma_f32_16x16x32_bf16 v[30:33], v[142:145], v[222:225], v[30:33]
	v_mfma_f32_16x16x32_bf16 v[22:25], v[150:153], v[222:225], v[22:25]
	v_mfma_f32_16x16x32_bf16 v[14:17], v[142:145], v[230:233], v[14:17]
	v_mfma_f32_16x16x32_bf16 v[6:9], v[150:153], v[230:233], v[6:9]
	v_mfma_f32_16x16x32_bf16 v[62:65], v[146:149], v[196:199], v[62:65]
	v_mfma_f32_16x16x32_bf16 v[54:57], v[154:157], v[196:199], v[54:57]
	v_mfma_f32_16x16x32_bf16 v[46:49], v[146:149], v[218:221], v[46:49]
	v_mfma_f32_16x16x32_bf16 v[38:41], v[154:157], v[218:221], v[38:41]
	v_mfma_f32_16x16x32_bf16 v[30:33], v[146:149], v[226:229], v[30:33]
	v_mfma_f32_16x16x32_bf16 v[22:25], v[154:157], v[226:229], v[22:25]
	v_mfma_f32_16x16x32_bf16 v[14:17], v[146:149], v[234:237], v[14:17]
	v_mfma_f32_16x16x32_bf16 v[6:9], v[154:157], v[234:237], v[6:9]
	v_mfma_f32_16x16x32_bf16 v[58:61], v[164:167], v[192:195], v[58:61]
	v_mfma_f32_16x16x32_bf16 v[50:53], v[184:187], v[192:195], v[50:53]
	v_mfma_f32_16x16x32_bf16 v[42:45], v[164:167], v[200:203], v[42:45]
	v_mfma_f32_16x16x32_bf16 v[34:37], v[184:187], v[200:203], v[34:37]
	v_mfma_f32_16x16x32_bf16 v[26:29], v[164:167], v[222:225], v[26:29]
	v_mfma_f32_16x16x32_bf16 v[18:21], v[184:187], v[222:225], v[18:21]
	v_mfma_f32_16x16x32_bf16 v[10:13], v[164:167], v[230:233], v[10:13]
	v_mfma_f32_16x16x32_bf16 v[2:5], v[184:187], v[230:233], v[2:5]
	v_mfma_f32_16x16x32_bf16 v[58:61], v[180:183], v[196:199], v[58:61]
	v_mfma_f32_16x16x32_bf16 v[50:53], v[188:191], v[196:199], v[50:53]
	v_mfma_f32_16x16x32_bf16 v[42:45], v[180:183], v[218:221], v[42:45]
	v_mfma_f32_16x16x32_bf16 v[34:37], v[188:191], v[218:221], v[34:37]
	v_mfma_f32_16x16x32_bf16 v[26:29], v[180:183], v[226:229], v[26:29]
	v_mfma_f32_16x16x32_bf16 v[18:21], v[188:191], v[226:229], v[18:21]
	v_mfma_f32_16x16x32_bf16 v[10:13], v[180:183], v[234:237], v[10:13]
	v_mfma_f32_16x16x32_bf16 v[2:5], v[188:191], v[234:237], v[2:5]
	s_barrier
; #define PG8_STAGE(bufoff, gbase, voff) do { _Pragma("unroll") for (int _i = 0; _i < 2; ++_i) \
;         __builtin_amdgcn_global_load_lds((const unsigned*)((const char*)(gbase) + (voff)[_i]), (PG8_LAS unsigned*)(lds + (bufoff) + ldsw + _i * 8192), 16, 0, 0); } while (0)
; #define PG8_LDA(dst, b, h) do { _Pragma("unroll") for (int m = 0; m < 4; ++m) _Pragma("unroll") for (int k = 0; k < 2; ++k) dst[m][k] = *(const PG8_LAS bf16x8*)(lds + PG8_SA(b, h) + aoff + m * 2048 + k * 1024); } while (0)
; #define PG8_LDB(dst, b, h) do { _Pragma("unroll") for (int n = 0; n < 2; ++n) _Pragma("unroll") for (int k = 0; k < 2; ++k) dst[n][k] = *(const PG8_LAS bf16x8*)(lds + PG8_SB(b, h) + boff + n * 2048 + k * 1024); } while (0)
; #define PG8_MMA(ai, bj, At, Bt) do { __builtin_amdgcn_s_setprio(1); _Pragma("unroll") for (int m = 0; m < 4; ++m) _Pragma("unroll") for (int n = 0; n < 2; ++n) _Pragma("unroll") for (int k = 0; k < 2; ++k) \
;         acc[ai][bj][m][n] = __builtin_amdgcn_mfma_f32_16x16x32_bf16(Bt[n][k], At[m][k], acc[ai][bj][m][n], 0, 0, 0); __builtin_amdgcn_s_setprio(0); } while (0)
; #define PG8_WAIT_V(n) asm volatile("s_waitcnt vmcnt(" #n ")" ::: "memory")
; #define PG8_WAIT_L(n) asm volatile("s_waitcnt lgkmcnt(" #n ")" ::: "memory")
; #define PG8_BAR __builtin_amdgcn_s_barrier()
; #define PG8_SCHED __builtin_amdgcn_sched_barrier(0)
; template <class Epi, class Sched, bool ALIGN_EPI = false, bool SP2 = false>
; __device__ __forceinline__ void gemm_phase(PG8_LAS unsigned char* lds, const Gemm g, const Sched& S, const Epi& E) {
;     ...
;             PG8_LDB(B0, 1, 0); PG8_LDB(B1, 1, 1); PG8_SCHED; PG8_LDA(At, 1, 0); PG8_STAGE(PG8_SA(0, 1), a2 + hstep, voffA);
;             PG8_WAIT_V(8); PG8_WAIT_L(0); PG8_BAR; PG8_MMA(0, 0, At, B0); PG8_MMA(0, 1, At, B1); PG8_BAR; PG8_SCHED;
;             PG8_LDA(At, 1, 1); PG8_STAGE(PG8_SB(1, 0), b3, voffB); PG8_STAGE(PG8_SB(1, 1), b3 + hstep, voffB); PG8_STAGE(PG8_SA(1, 0), a3, voffA);
;             PG8_WAIT_V(8); PG8_WAIT_L(0); PG8_BAR; PG8_MMA(1, 0, At, B0); PG8_MMA(1, 1, At, B1); PG8_BAR; PG8_SCHED;
	s_add_i32 s54, 0, 0x18000
	s_add_i32 s55, 0, 0x1c000
	ds_read_b128 v[142:145], v159 offset:32768
	ds_read_b128 v[146:149], v159 offset:33792
	ds_read_b128 v[150:153], v159 offset:34816
	ds_read_b128 v[154:157], v159 offset:35840
	ds_read_b128 v[164:167], v159 offset:49152
	ds_read_b128 v[180:183], v159 offset:50176
	ds_read_b128 v[184:187], v159 offset:51200
	ds_read_b128 v[188:191], v159 offset:52224
	s_add_u32 s28, s28, 0x80000
	s_addc_u32 s29, s29, 0
	s_mov_b32 m0, s47
	ds_read_b128 v[192:195], v162 offset:32768
	ds_read_b128 v[196:199], v162 offset:33792
	ds_read_b128 v[200:203], v162 offset:34816
	ds_read_b128 v[218:221], v162 offset:35840
	ds_read_b128 v[222:225], v162 offset:36864
	ds_read_b128 v[226:229], v162 offset:37888
	ds_read_b128 v[230:233], v162 offset:38912
	ds_read_b128 v[234:237], v162 offset:39936
	global_load_lds_dwordx4 v134, s[28:29]
	s_mov_b32 m0, s48
	s_nop 0
	global_load_lds_dwordx4 v132, s[28:29]
	s_waitcnt vmcnt(8)
	s_waitcnt lgkmcnt(0)
	s_barrier
	v_mfma_f32_16x16x32_bf16 v[126:129], v[142:145], v[192:195], v[126:129]
	v_mfma_f32_16x16x32_bf16 v[118:121], v[150:153], v[192:195], v[118:121]
	v_mfma_f32_16x16x32_bf16 v[110:113], v[142:145], v[200:203], v[110:113]
	v_mfma_f32_16x16x32_bf16 v[102:105], v[150:153], v[200:203], v[102:105]
	v_mfma_f32_16x16x32_bf16 v[94:97], v[142:145], v[222:225], v[94:97]
	v_mfma_f32_16x16x32_bf16 v[86:89], v[150:153], v[222:225], v[86:89]
	v_mfma_f32_16x16x32_bf16 v[78:81], v[142:145], v[230:233], v[78:81]
	v_mfma_f32_16x16x32_bf16 v[70:73], v[150:153], v[230:233], v[70:73]
	v_mfma_f32_16x16x32_bf16 v[126:129], v[146:149], v[196:199], v[126:129]
	v_mfma_f32_16x16x32_bf16 v[118:121], v[154:157], v[196:199], v[118:121]
	v_mfma_f32_16x16x32_bf16 v[110:113], v[146:149], v[218:221], v[110:113]
	v_mfma_f32_16x16x32_bf16 v[102:105], v[154:157], v[218:221], v[102:105]
	v_mfma_f32_16x16x32_bf16 v[94:97], v[146:149], v[226:229], v[94:97]
	v_mfma_f32_16x16x32_bf16 v[86:89], v[154:157], v[226:229], v[86:89]
	v_mfma_f32_16x16x32_bf16 v[78:81], v[146:149], v[234:237], v[78:81]
	v_mfma_f32_16x16x32_bf16 v[70:73], v[154:157], v[234:237], v[70:73]
	v_mfma_f32_16x16x32_bf16 v[122:125], v[164:167], v[192:195], v[122:125]
	v_mfma_f32_16x16x32_bf16 v[114:117], v[184:187], v[192:195], v[114:117]
	v_mfma_f32_16x16x32_bf16 v[106:109], v[164:167], v[200:203], v[106:109]
	v_mfma_f32_16x16x32_bf16 v[98:101], v[184:187], v[200:203], v[98:101]
	v_mfma_f32_16x16x32_bf16 v[90:93], v[164:167], v[222:225], v[90:93]
	v_mfma_f32_16x16x32_bf16 v[82:85], v[184:187], v[222:225], v[82:85]
	v_mfma_f32_16x16x32_bf16 v[74:77], v[164:167], v[230:233], v[74:77]
	v_mfma_f32_16x16x32_bf16 v[66:69], v[184:187], v[230:233], v[66:69]
	v_mfma_f32_16x16x32_bf16 v[122:125], v[180:183], v[196:199], v[122:125]
	v_mfma_f32_16x16x32_bf16 v[114:117], v[188:191], v[196:199], v[114:117]
	v_mfma_f32_16x16x32_bf16 v[106:109], v[180:183], v[218:221], v[106:109]
	v_mfma_f32_16x16x32_bf16 v[98:101], v[188:191], v[218:221], v[98:101]
	v_mfma_f32_16x16x32_bf16 v[90:93], v[180:183], v[226:229], v[90:93]
	v_mfma_f32_16x16x32_bf16 v[82:85], v[188:191], v[226:229], v[82:85]
	v_mfma_f32_16x16x32_bf16 v[74:77], v[180:183], v[234:237], v[74:77]
	v_mfma_f32_16x16x32_bf16 v[66:69], v[188:191], v[234:237], v[66:69]
	s_barrier
	s_add_i32 s28, s54, s38
	s_add_i32 m0, s28, 0xffffff80
	ds_read_b128 v[192:195], v162 offset:49152
	ds_read_b128 v[196:199], v162 offset:50176
	ds_read_b128 v[200:203], v162 offset:51200
	ds_read_b128 v[218:221], v162 offset:52224
	ds_read_b128 v[222:225], v162 offset:53248
	ds_read_b128 v[226:229], v162 offset:54272
	ds_read_b128 v[230:233], v162 offset:55296
	ds_read_b128 v[234:237], v162 offset:56320
	global_load_lds_dwordx4 v0, s[26:27] offset:128
	s_add_i32 m0, s28, 0x2000
	s_add_u32 s26, s26, 0x80080
	v_lshl_add_u64 v[238:239], v[240:241], 0, s[34:35]
	s_addc_u32 s27, s27, 0
	s_add_i32 s28, s55, s38
	global_load_lds_dwordx4 v[238:239], off
	s_mov_b32 m0, s28
	s_nop 0
	global_load_lds_dwordx4 v0, s[26:27]
	s_add_i32 m0, s28, 0x2000
	s_nop 0
	global_load_lds_dwordx4 v130, s[26:27]
	v_lshl_add_u64 v[238:239], v[242:243], 0, s[34:35]
	s_mov_b32 m0, s4
	s_nop 0
	global_load_lds_dwordx4 v[238:239], off
	v_lshl_add_u64 v[238:239], v[244:245], 0, s[34:35]
	s_mov_b32 m0, s49
	s_nop 0
	global_load_lds_dwordx4 v[238:239], off
	s_waitcnt vmcnt(8)
	s_waitcnt lgkmcnt(0)
	s_barrier
	v_mfma_f32_16x16x32_bf16 v[62:65], v[142:145], v[192:195], v[62:65]
	v_mfma_f32_16x16x32_bf16 v[54:57], v[150:153], v[192:195], v[54:57]
	v_mfma_f32_16x16x32_bf16 v[46:49], v[142:145], v[200:203], v[46:49]
	v_mfma_f32_16x16x32_bf16 v[38:41], v[150:153], v[200:203], v[38:41]
	v_mfma_f32_16x16x32_bf16 v[30:33], v[142:145], v[222:225], v[30:33]
	v_mfma_f32_16x16x32_bf16 v[22:25], v[150:153], v[222:225], v[22:25]
	v_mfma_f32_16x16x32_bf16 v[14:17], v[142:145], v[230:233], v[14:17]
	v_mfma_f32_16x16x32_bf16 v[6:9], v[150:153], v[230:233], v[6:9]
	v_mfma_f32_16x16x32_bf16 v[62:65], v[146:149], v[196:199], v[62:65]
	v_mfma_f32_16x16x32_bf16 v[54:57], v[154:157], v[196:199], v[54:57]
	v_mfma_f32_16x16x32_bf16 v[46:49], v[146:149], v[218:221], v[46:49]
	v_mfma_f32_16x16x32_bf16 v[38:41], v[154:157], v[218:221], v[38:41]
	v_mfma_f32_16x16x32_bf16 v[30:33], v[146:149], v[226:229], v[30:33]
	v_mfma_f32_16x16x32_bf16 v[22:25], v[154:157], v[226:229], v[22:25]
	v_mfma_f32_16x16x32_bf16 v[14:17], v[146:149], v[234:237], v[14:17]
	v_mfma_f32_16x16x32_bf16 v[6:9], v[154:157], v[234:237], v[6:9]
	v_mfma_f32_16x16x32_bf16 v[58:61], v[164:167], v[192:195], v[58:61]
	v_mfma_f32_16x16x32_bf16 v[50:53], v[184:187], v[192:195], v[50:53]
	v_mfma_f32_16x16x32_bf16 v[42:45], v[164:167], v[200:203], v[42:45]
	v_mfma_f32_16x16x32_bf16 v[34:37], v[184:187], v[200:203], v[34:37]
	v_mfma_f32_16x16x32_bf16 v[26:29], v[164:167], v[222:225], v[26:29]
	v_mfma_f32_16x16x32_bf16 v[18:21], v[184:187], v[222:225], v[18:21]
	v_mfma_f32_16x16x32_bf16 v[10:13], v[164:167], v[230:233], v[10:13]
	v_mfma_f32_16x16x32_bf16 v[2:5], v[184:187], v[230:233], v[2:5]
	v_mfma_f32_16x16x32_bf16 v[58:61], v[180:183], v[196:199], v[58:61]
	v_mfma_f32_16x16x32_bf16 v[50:53], v[188:191], v[196:199], v[50:53]
	v_mfma_f32_16x16x32_bf16 v[42:45], v[180:183], v[218:221], v[42:45]
	v_mfma_f32_16x16x32_bf16 v[34:37], v[188:191], v[218:221], v[34:37]
	v_mfma_f32_16x16x32_bf16 v[26:29], v[180:183], v[226:229], v[26:29]
	v_mfma_f32_16x16x32_bf16 v[18:21], v[188:191], v[226:229], v[18:21]
	v_mfma_f32_16x16x32_bf16 v[10:13], v[180:183], v[234:237], v[10:13]
	v_mfma_f32_16x16x32_bf16 v[2:5], v[188:191], v[234:237], v[2:5]
	s_barrier
	s_add_i32 s77, s77, 2
	s_add_u32 s16, s16, 0x100
	s_addc_u32 s17, s17, 0
	s_add_u32 s53, s53, 0x100
	s_addc_u32 s73, s73, 0
	s_cmp_gt_u32 s77, 29
	s_cbranch_scc0 .LBB0_659
	s_and_b64 vcc, exec, s[18:19]
	s_cbranch_vccz .LBB0_662
	s_barrier

; #define PG8_WAIT_V(n) asm volatile("s_waitcnt vmcnt(" #n ")" ::: "memory")
; #define PG8_BAR __builtin_amdgcn_s_barrier()
; template <class Epi, class Sched, bool ALIGN_EPI = false, bool SP2 = false>
; __device__ __forceinline__ void gemm_phase(PG8_LAS unsigned char* lds, const Gemm g, const Sched& S, const Epi& E) {
;     ...
;     for (int i = 0; i < 2; ++i) { int R, C; stage_rc(tid * 16 + i * 8192, R, C); const int Rb = Epi::PERM ? ((R & ~31) + perm32(R & 31)) : R;
;         voffA[i] = (unsigned)(R * K + C) * 2u; voffB[i] = (unsigned)(Rb * K + C) * 2u; }
;     const size_t kstep = (size_t)(BK * 2);
;     const size_t hstep = (size_t)HALF * K * 2;
;     const size_t tstep = 2 * hstep;
;     const unsigned ldsw = (unsigned)wid * 1024u;
;     const int aoff = lds_byte(wr * 64 + fr, fq * 8), boff = lds_byte(wc * 32 + fr, fq * 8);
;     ...
;     Unit cur, nxt; int ui = 0;
;     if (!S.next(0, cur)) return;
;     f32x4 acc[2][2][4][2];
; #pragma unroll
;     for (int a = 0; a < 2; ++a)
; #pragma unroll
;         for (int b = 0; b < 2; ++b)
; #pragma unroll
;             for (int m = 0; m < 4; ++m)
; #pragma unroll
;                 for (int n = 0; n < 2; ++n) acc[a][b][m][n] = (f32x4){0.f, 0.f, 0.f, 0.f};
;     bf16x8 At[4][2], B0[2][2], B1[2][2];
;     const char* cA = (const char*)(cur.part ? g.A1 : g.A) + (size_t)cur.pm * tstep; const char* cB = (const char*)(cur.part ? g.Bt1 : g.Bt) + (size_t)cur.pn * tstep;
;     S.a_ready(cur);
;     if constexpr (SP2) {
;         PG8_STAGE(PG8_SB(0, 0), cB, voffB); PG8_STAGE(PG8_SB(0, 1), cB + hstep, voffB); PG8_STAGE(PG8_SA(0, 0), cA, voffA); PG8_STAGE(PG8_SA(0, 1), cA + hstep, voffA);
;         E.after_first_stage(tid);
;         if (wr == 1) PG8_BAR;
;         PG8_WAIT_V(2); PG8_BAR;
;         PG8_STAGE(PG8_SB(1, 0), cB + kstep, voffB); PG8_STAGE(PG8_SA(1, 0), cA + kstep, voffA); PG8_STAGE(PG8_SB(1, 1), cB + hstep + kstep, voffB);
;         PG8_WAIT_V(6); PG8_BAR;
;     } else {
;         PG8_STAGE(PG8_SB(0, 0), cB, voffB); PG8_STAGE(PG8_SA(0, 0), cA, voffA); PG8_STAGE(PG8_SB(0, 1), cB + hstep, voffB); PG8_STAGE(PG8_SA(0, 1), cA + hstep, voffA);
;         if (wr == 1) PG8_BAR;
;         PG8_WAIT_V(4); PG8_BAR;
;         PG8_STAGE(PG8_SB(1, 0), cB + kstep, voffB); PG8_STAGE(PG8_SA(1, 0), cA + kstep, voffA); PG8_STAGE(PG8_SB(1, 1), cB + hstep + kstep, voffB);
;         PG8_WAIT_V(6); PG8_BAR;
;     }
.LBB0_788:
	s_lshl_b32 s4, s64, 17
	s_xor_b32 s4, s4, 0x20000
	s_lshl_b64 s[18:19], s[4:5], 2
	v_readlane_b32 s4, v250, 40
	v_bfe_u32 v15, v14, 4, 2
	v_readlane_b32 s22, v248, 32
	s_add_u32 s4, s4, s18
	v_readlane_b32 s17, v250, 41
	v_and_b32_e32 v20, 15, v14
	v_lshlrev_b32_e32 v22, 4, v15
	v_lshlrev_b32_e32 v14, 2, v14
	v_mov_b32_e32 v163, v1
	v_readlane_b32 s23, v248, 33
	s_addc_u32 s50, s17, s19
	s_and_b32 s17, s7, 3
	v_lshl_or_b32 v198, s6, 6, v20
	v_lshl_or_b32 v23, v20, 6, v22
	s_lshl_b32 s6, s6, 13
	v_and_b32_e32 v14, 32, v14
	s_add_i32 m0, s46, 0x18000
	v_lshl_add_u64 v[2:3], v[2:3], 0, s[34:35]
	v_lshl_add_u64 v[16:17], s[22:23], 0, v[162:163]
	v_mov_b32_e32 v161, v1
	v_bitop3_b32 v24, v23, s6, v14 bitop3:0xde
	s_lshl_b32 s6, s17, 12
	s_waitcnt vmcnt(2)
	s_barrier
	global_load_lds_dwordx4 v[2:3], off
	v_lshl_add_u64 v[2:3], v[4:5], 0, s[34:35]
	s_add_i32 m0, s46, 0x1a000
	s_add_i32 s51, s46, 0x8000
	s_add_i32 s52, s46, 0xa000
	v_lshl_add_u64 v[18:19], s[22:23], 0, v[160:161]
	v_bitop3_b32 v199, v23, s6, v14 bitop3:0xde
	v_add_u32_e32 v199, 0x10000, v199
	global_load_lds_dwordx4 v[2:3], off
	v_lshl_add_u64 v[2:3], v[16:17], 0, s[34:35]
	s_mov_b32 m0, s51
	s_add_u32 s6, s24, 0x160080
	global_load_lds_dwordx4 v[2:3], off
	v_lshl_add_u64 v[2:3], v[18:19], 0, s[34:35]
	s_mov_b32 m0, s52
	s_addc_u32 s7, s25, 0
	global_load_lds_dwordx4 v[2:3], off
	s_add_i32 m0, s46, 0x1c000
	v_lshl_add_u64 v[2:3], s[6:7], 0, v[0:1]
	global_load_lds_dwordx4 v[2:3], off
	v_lshl_add_u64 v[2:3], s[6:7], 0, v[158:159]
	s_add_i32 m0, s46, 0x1e000
	s_cmpk_lt_u32 s16, 0x100
	global_load_lds_dwordx4 v[2:3], off
	s_cselect_b64 s[6:7], -1, 0
	s_and_b32 s16, s16, 0xffffff00
	s_lshl_b32 s18, s17, 6
	s_or_b32 s16, s18, s16
	v_or3_b32 v164, s16, v22, v20
	s_movk_i32 s16, 0x100
	v_cmp_gt_i32_e64 s[40:41], s16, v164
	s_lshl_b32 s16, s17, 2
	s_add_i32 s16, s16, 0
	s_movk_i32 s19, 0x1600
	v_lshlrev_b32_e32 v21, 3, v15
	s_add_i32 s16, s16, 0x22c00
	v_lshrrev_b32_e32 v3, 1, v11
	v_mul_lo_u32 v2, v10, s19
	s_mov_b32 s18, 0x16000
	v_lshl_or_b32 v200, s17, 5, v21
	v_lshl_add_u32 v201, v198, 4, s16
	v_mad_u64_u32 v[2:3], s[16:17], v3, s18, v[2:3]
	v_or_b32_e32 v2, v2, v12
	v_add_lshl_u32 v2, v2, v13, 1
	v_mov_b32_e32 v3, v1
	s_mov_b64 s[20:21], 0x160080
	v_lshl_add_u64 v[166:167], v[2:3], 0, s[20:21]
	v_lshrrev_b32_e32 v3, 1, v6
	v_mul_lo_u32 v2, v7, s19
	v_mad_u64_u32 v[2:3], s[16:17], v3, s18, v[2:3]
	v_or_b32_e32 v2, v2, v8
	s_waitcnt vmcnt(6)
	v_lshlrev_b32_e32 v4, 4, v164
	v_add_lshl_u32 v2, v2, v9, 1
	v_mov_b32_e32 v3, v1
	v_lshl_add_u64 v[180:181], v[2:3], 0, s[20:21]
	v_add_u32_e32 v2, 0, v4
	v_readlane_b32 s18, v248, 30
	s_mov_b32 s53, 0
	v_cmp_eq_u32_e64 s[38:39], 0, v15
	v_ashrrev_i32_e32 v165, 31, v164
	v_add_u32_e32 v202, 0, v24
	v_add_u32_e32 v203, 0x22c00, v2
	v_readlane_b32 s16, v248, 11
	s_mov_b32 s17, s18
	s_barrier
	v_readlane_b32 s19, v248, 31
	s_branch .LBB0_791

; #define PG8_STAGE(bufoff, gbase, voff) do { _Pragma("unroll") for (int _i = 0; _i < 2; ++_i) \
;         __builtin_amdgcn_global_load_lds((const unsigned*)((const char*)(gbase) + (voff)[_i]), (PG8_LAS unsigned*)(lds + (bufoff) + ldsw + _i * 8192), 16, 0, 0); } while (0)
; #define PG8_LDA(dst, b, h) do { _Pragma("unroll") for (int m = 0; m < 4; ++m) _Pragma("unroll") for (int k = 0; k < 2; ++k) dst[m][k] = *(const PG8_LAS bf16x8*)(lds + PG8_SA(b, h) + aoff + m * 2048 + k * 1024); } while (0)
; #define PG8_LDB(dst, b, h) do { _Pragma("unroll") for (int n = 0; n < 2; ++n) _Pragma("unroll") for (int k = 0; k < 2; ++k) dst[n][k] = *(const PG8_LAS bf16x8*)(lds + PG8_SB(b, h) + boff + n * 2048 + k * 1024); } while (0)
; #define PG8_MMA(ai, bj, At, Bt) do { __builtin_amdgcn_s_setprio(1); _Pragma("unroll") for (int m = 0; m < 4; ++m) _Pragma("unroll") for (int n = 0; n < 2; ++n) _Pragma("unroll") for (int k = 0; k < 2; ++k) \
;         acc[ai][bj][m][n] = __builtin_amdgcn_mfma_f32_16x16x32_bf16(Bt[n][k], At[m][k], acc[ai][bj][m][n], 0, 0, 0); __builtin_amdgcn_s_setprio(0); } while (0)
; #define PG8_WAIT_V(n) asm volatile("s_waitcnt vmcnt(" #n ")" ::: "memory")
; #define PG8_WAIT_L(n) asm volatile("s_waitcnt lgkmcnt(" #n ")" ::: "memory")
; template <class Epi, class Sched, bool ALIGN_EPI = false, bool SP2 = false>
; __device__ __forceinline__ void gemm_phase(PG8_LAS unsigned char* lds, const Gemm g, const Sched& S, const Epi& E) {
;     ...
;             const bool last = (t == nt - 2);
;             const char* a1 = cA + (size_t)(t + 1) * kstep;
;             const char* a2 = last ? nA : cA + (size_t)(t + 2) * kstep; const char* b2 = last ? nB : cB + (size_t)(t + 2) * kstep;
;             const char* a3 = a2 + kstep; const char* b3 = b2 + kstep;
;             if (last && has_next) S.a_ready(nxt);
;             if constexpr (SP2) {
;             PG8_LDB(B0, 0, 0); PG8_LDB(B1, 0, 1); PG8_SCHED; PG8_LDA(At, 0, 0); PG8_STAGE(PG8_SA(1, 1), a1 + hstep, voffA);
;             PG8_WAIT_V(8); PG8_WAIT_L(0); PG8_BAR; PG8_MMA(0, 0, At, B0); PG8_MMA(0, 1, At, B1); PG8_BAR; PG8_SCHED;
;             PG8_LDA(At, 0, 1); PG8_STAGE(PG8_SB(0, 0), b2, voffB); PG8_STAGE(PG8_SB(0, 1), b2 + hstep, voffB); PG8_STAGE(PG8_SA(0, 0), a2, voffA);
;             PG8_WAIT_V(8); PG8_WAIT_L(0); PG8_BAR; PG8_MMA(1, 0, At, B0); PG8_MMA(1, 1, At, B1); PG8_BAR; PG8_SCHED;
.LBB0_802:
	s_add_u32 s24, s22, 0x100
	s_addc_u32 s25, s23, 0
	s_add_i32 s54, 0, 0x10000
	s_cmpk_eq_i32 s78, 0x54
	s_cselect_b32 s29, s19, s25
	s_cselect_b32 s28, s18, s24
	s_cselect_b32 s27, s21, s45
	s_cselect_b32 s26, s20, s44
	s_add_i32 s55, 0, 0x14000
	ds_read_b128 v[122:125], v199
	ds_read_b128 v[134:137], v199 offset:1024
	ds_read_b128 v[138:141], v199 offset:2048
	ds_read_b128 v[142:145], v199 offset:3072
	ds_read_b128 v[146:149], v199 offset:16384
	ds_read_b128 v[150:153], v199 offset:17408
	ds_read_b128 v[154:157], v199 offset:18432
	ds_read_b128 v[182:185], v199 offset:19456
	s_add_i32 m0, s46, 0xc000
	ds_read_b128 v[186:189], v202
	ds_read_b128 v[190:193], v202 offset:1024
	ds_read_b128 v[194:197], v202 offset:2048
	ds_read_b128 v[218:221], v202 offset:3072
	ds_read_b128 v[222:225], v202 offset:4096
	ds_read_b128 v[226:229], v202 offset:5120
	ds_read_b128 v[230:233], v202 offset:6144
	ds_read_b128 v[234:237], v202 offset:7168
	global_load_lds_dwordx4 v166, s[22:23]
	s_add_i32 m0, s46, 0xe000
	s_nop 0
	global_load_lds_dwordx4 v180, s[22:23]
	s_waitcnt vmcnt(8)
	s_waitcnt lgkmcnt(0)
	s_barrier
	v_mfma_f32_16x16x32_bf16 v[130:133], v[122:125], v[186:189], v[130:133]
	v_mfma_f32_16x16x32_bf16 v[126:129], v[138:141], v[186:189], v[126:129]
	v_mfma_f32_16x16x32_bf16 v[110:113], v[122:125], v[194:197], v[110:113]
	v_mfma_f32_16x16x32_bf16 v[106:109], v[138:141], v[194:197], v[106:109]
	v_mfma_f32_16x16x32_bf16 v[94:97], v[122:125], v[222:225], v[94:97]
	v_mfma_f32_16x16x32_bf16 v[90:93], v[138:141], v[222:225], v[90:93]
	v_mfma_f32_16x16x32_bf16 v[78:81], v[122:125], v[230:233], v[78:81]
	v_mfma_f32_16x16x32_bf16 v[74:77], v[138:141], v[230:233], v[74:77]
	v_mfma_f32_16x16x32_bf16 v[130:133], v[134:137], v[190:193], v[130:133]
	v_mfma_f32_16x16x32_bf16 v[126:129], v[142:145], v[190:193], v[126:129]
	v_mfma_f32_16x16x32_bf16 v[110:113], v[134:137], v[218:221], v[110:113]
	v_mfma_f32_16x16x32_bf16 v[106:109], v[142:145], v[218:221], v[106:109]
	v_mfma_f32_16x16x32_bf16 v[94:97], v[134:137], v[226:229], v[94:97]
	v_mfma_f32_16x16x32_bf16 v[90:93], v[142:145], v[226:229], v[90:93]
	v_mfma_f32_16x16x32_bf16 v[78:81], v[134:137], v[234:237], v[78:81]
	v_mfma_f32_16x16x32_bf16 v[74:77], v[142:145], v[234:237], v[74:77]
	v_mfma_f32_16x16x32_bf16 v[118:121], v[146:149], v[186:189], v[118:121]
	v_mfma_f32_16x16x32_bf16 v[114:117], v[154:157], v[186:189], v[114:117]
	v_mfma_f32_16x16x32_bf16 v[102:105], v[146:149], v[194:197], v[102:105]
	v_mfma_f32_16x16x32_bf16 v[98:101], v[154:157], v[194:197], v[98:101]
	v_mfma_f32_16x16x32_bf16 v[86:89], v[146:149], v[222:225], v[86:89]
	v_mfma_f32_16x16x32_bf16 v[82:85], v[154:157], v[222:225], v[82:85]
	v_mfma_f32_16x16x32_bf16 v[70:73], v[146:149], v[230:233], v[70:73]
	v_mfma_f32_16x16x32_bf16 v[66:69], v[154:157], v[230:233], v[66:69]
	v_mfma_f32_16x16x32_bf16 v[118:121], v[150:153], v[190:193], v[118:121]
	v_mfma_f32_16x16x32_bf16 v[114:117], v[182:185], v[190:193], v[114:117]
	v_mfma_f32_16x16x32_bf16 v[102:105], v[150:153], v[218:221], v[102:105]
	v_mfma_f32_16x16x32_bf16 v[98:101], v[182:185], v[218:221], v[98:101]
	v_mfma_f32_16x16x32_bf16 v[86:89], v[150:153], v[226:229], v[86:89]
	v_mfma_f32_16x16x32_bf16 v[82:85], v[182:185], v[226:229], v[82:85]
	v_mfma_f32_16x16x32_bf16 v[70:73], v[150:153], v[234:237], v[70:73]
	v_mfma_f32_16x16x32_bf16 v[66:69], v[182:185], v[234:237], v[66:69]
	s_barrier
	s_add_i32 s22, s54, s2
	s_mov_b32 m0, s22
	ds_read_b128 v[186:189], v202 offset:16384
	ds_read_b128 v[190:193], v202 offset:17408
	ds_read_b128 v[194:197], v202 offset:18432
	ds_read_b128 v[218:221], v202 offset:19456
	ds_read_b128 v[222:225], v202 offset:20480
	ds_read_b128 v[226:229], v202 offset:21504
	ds_read_b128 v[230:233], v202 offset:22528
	ds_read_b128 v[234:237], v202 offset:23552
	global_load_lds_dwordx4 v0, s[26:27]
	s_add_i32 m0, s22, 0x2000
	s_add_u32 s22, s26, 0x160000
	v_lshl_add_u64 v[240:241], s[26:27], 0, v[158:159]
	s_addc_u32 s23, s27, 0
	s_add_i32 s54, s55, s2
	global_load_lds_dwordx4 v158, s[26:27]
	s_mov_b32 m0, s54
	s_nop 0
	global_load_lds_dwordx4 v0, s[22:23]
	s_add_i32 m0, s54, 0x2000
	s_nop 0
	global_load_lds_dwordx4 v158, s[22:23]
	s_mov_b32 m0, s46
	s_nop 0
	global_load_lds_dwordx4 v162, s[28:29]
	s_mov_b32 m0, s47
	s_nop 0
	global_load_lds_dwordx4 v160, s[28:29]
	s_waitcnt vmcnt(8)
	s_waitcnt lgkmcnt(0)
	s_barrier
	v_mfma_f32_16x16x32_bf16 v[62:65], v[122:125], v[186:189], v[62:65]
	v_mfma_f32_16x16x32_bf16 v[58:61], v[138:141], v[186:189], v[58:61]
	v_mfma_f32_16x16x32_bf16 v[46:49], v[122:125], v[194:197], v[46:49]
	v_mfma_f32_16x16x32_bf16 v[42:45], v[138:141], v[194:197], v[42:45]
	v_mfma_f32_16x16x32_bf16 v[30:33], v[122:125], v[222:225], v[30:33]
	v_mfma_f32_16x16x32_bf16 v[26:29], v[138:141], v[222:225], v[26:29]
	v_mfma_f32_16x16x32_bf16 v[14:17], v[122:125], v[230:233], v[14:17]
	v_mfma_f32_16x16x32_bf16 v[10:13], v[138:141], v[230:233], v[10:13]
	v_mfma_f32_16x16x32_bf16 v[62:65], v[134:137], v[190:193], v[62:65]
	v_mfma_f32_16x16x32_bf16 v[58:61], v[142:145], v[190:193], v[58:61]
	v_mfma_f32_16x16x32_bf16 v[46:49], v[134:137], v[218:221], v[46:49]
	v_mfma_f32_16x16x32_bf16 v[42:45], v[142:145], v[218:221], v[42:45]
	v_mfma_f32_16x16x32_bf16 v[30:33], v[134:137], v[226:229], v[30:33]
	v_mfma_f32_16x16x32_bf16 v[26:29], v[142:145], v[226:229], v[26:29]
	v_mfma_f32_16x16x32_bf16 v[14:17], v[134:137], v[234:237], v[14:17]
	v_mfma_f32_16x16x32_bf16 v[10:13], v[142:145], v[234:237], v[10:13]
	v_mfma_f32_16x16x32_bf16 v[54:57], v[146:149], v[186:189], v[54:57]
	v_mfma_f32_16x16x32_bf16 v[50:53], v[154:157], v[186:189], v[50:53]
	v_mfma_f32_16x16x32_bf16 v[38:41], v[146:149], v[194:197], v[38:41]
	v_mfma_f32_16x16x32_bf16 v[34:37], v[154:157], v[194:197], v[34:37]
	v_mfma_f32_16x16x32_bf16 v[22:25], v[146:149], v[222:225], v[22:25]
	v_mfma_f32_16x16x32_bf16 v[18:21], v[154:157], v[222:225], v[18:21]
	v_mfma_f32_16x16x32_bf16 v[6:9], v[146:149], v[230:233], v[6:9]
	v_mfma_f32_16x16x32_bf16 v[2:5], v[154:157], v[230:233], v[2:5]
	v_mfma_f32_16x16x32_bf16 v[54:57], v[150:153], v[190:193], v[54:57]
	v_mfma_f32_16x16x32_bf16 v[50:53], v[182:185], v[190:193], v[50:53]
	v_mfma_f32_16x16x32_bf16 v[38:41], v[150:153], v[218:221], v[38:41]
	v_mfma_f32_16x16x32_bf16 v[34:37], v[182:185], v[218:221], v[34:37]
	v_mfma_f32_16x16x32_bf16 v[22:25], v[150:153], v[226:229], v[22:25]
	v_mfma_f32_16x16x32_bf16 v[18:21], v[182:185], v[226:229], v[18:21]
	v_mfma_f32_16x16x32_bf16 v[6:9], v[150:153], v[234:237], v[6:9]
	v_mfma_f32_16x16x32_bf16 v[2:5], v[182:185], v[234:237], v[2:5]
	s_barrier
; #define PG8_STAGE(bufoff, gbase, voff) do { _Pragma("unroll") for (int _i = 0; _i < 2; ++_i) \
;         __builtin_amdgcn_global_load_lds((const unsigned*)((const char*)(gbase) + (voff)[_i]), (PG8_LAS unsigned*)(lds + (bufoff) + ldsw + _i * 8192), 16, 0, 0); } while (0)
; #define PG8_LDA(dst, b, h) do { _Pragma("unroll") for (int m = 0; m < 4; ++m) _Pragma("unroll") for (int k = 0; k < 2; ++k) dst[m][k] = *(const PG8_LAS bf16x8*)(lds + PG8_SA(b, h) + aoff + m * 2048 + k * 1024); } while (0)
; #define PG8_LDB(dst, b, h) do { _Pragma("unroll") for (int n = 0; n < 2; ++n) _Pragma("unroll") for (int k = 0; k < 2; ++k) dst[n][k] = *(const PG8_LAS bf16x8*)(lds + PG8_SB(b, h) + boff + n * 2048 + k * 1024); } while (0)
; #define PG8_MMA(ai, bj, At, Bt) do { __builtin_amdgcn_s_setprio(1); _Pragma("unroll") for (int m = 0; m < 4; ++m) _Pragma("unroll") for (int n = 0; n < 2; ++n) _Pragma("unroll") for (int k = 0; k < 2; ++k) \
;         acc[ai][bj][m][n] = __builtin_amdgcn_mfma_f32_16x16x32_bf16(Bt[n][k], At[m][k], acc[ai][bj][m][n], 0, 0, 0); __builtin_amdgcn_s_setprio(0); } while (0)
; #define PG8_WAIT_V(n) asm volatile("s_waitcnt vmcnt(" #n ")" ::: "memory")
; #define PG8_WAIT_L(n) asm volatile("s_waitcnt lgkmcnt(" #n ")" ::: "memory")
; #define PG8_BAR __builtin_amdgcn_s_barrier()
; #define PG8_SCHED __builtin_amdgcn_sched_barrier(0)
; template <class Epi, class Sched, bool ALIGN_EPI = false, bool SP2 = false>
; __device__ __forceinline__ void gemm_phase(PG8_LAS unsigned char* lds, const Gemm g, const Sched& S, const Epi& E) {
;     ...
;             PG8_LDB(B0, 1, 0); PG8_LDB(B1, 1, 1); PG8_SCHED; PG8_LDA(At, 1, 0); PG8_STAGE(PG8_SA(0, 1), a2 + hstep, voffA);
;             PG8_WAIT_V(8); PG8_WAIT_L(0); PG8_BAR; PG8_MMA(0, 0, At, B0); PG8_MMA(0, 1, At, B1); PG8_BAR; PG8_SCHED;
;             PG8_LDA(At, 1, 1); PG8_STAGE(PG8_SB(1, 0), b3, voffB); PG8_STAGE(PG8_SB(1, 1), b3 + hstep, voffB); PG8_STAGE(PG8_SA(1, 0), a3, voffA);
;             PG8_WAIT_V(8); PG8_WAIT_L(0); PG8_BAR; PG8_MMA(1, 0, At, B0); PG8_MMA(1, 1, At, B1); PG8_BAR; PG8_SCHED;
	s_add_i32 s54, 0, 0x18000
	s_add_i32 s55, 0, 0x1c000
	ds_read_b128 v[122:125], v199 offset:32768
	ds_read_b128 v[134:137], v199 offset:33792
	ds_read_b128 v[138:141], v199 offset:34816
	ds_read_b128 v[142:145], v199 offset:35840
	ds_read_b128 v[146:149], v199 offset:49152
	ds_read_b128 v[150:153], v199 offset:50176
	ds_read_b128 v[154:157], v199 offset:51200
	ds_read_b128 v[182:185], v199 offset:52224
	s_add_u32 s22, s28, 0x160000
	s_addc_u32 s23, s29, 0
	s_mov_b32 m0, s48
	ds_read_b128 v[186:189], v202 offset:32768
	ds_read_b128 v[190:193], v202 offset:33792
	ds_read_b128 v[194:197], v202 offset:34816
	ds_read_b128 v[218:221], v202 offset:35840
	ds_read_b128 v[222:225], v202 offset:36864
	ds_read_b128 v[226:229], v202 offset:37888
	ds_read_b128 v[230:233], v202 offset:38912
	ds_read_b128 v[234:237], v202 offset:39936
	global_load_lds_dwordx4 v162, s[22:23]
	s_mov_b32 m0, s49
	s_nop 0
	global_load_lds_dwordx4 v160, s[22:23]
	s_waitcnt vmcnt(8)
	s_waitcnt lgkmcnt(0)
	s_barrier
	v_mfma_f32_16x16x32_bf16 v[130:133], v[122:125], v[186:189], v[130:133]
	v_mfma_f32_16x16x32_bf16 v[126:129], v[138:141], v[186:189], v[126:129]
	v_mfma_f32_16x16x32_bf16 v[110:113], v[122:125], v[194:197], v[110:113]
	v_mfma_f32_16x16x32_bf16 v[106:109], v[138:141], v[194:197], v[106:109]
	v_mfma_f32_16x16x32_bf16 v[94:97], v[122:125], v[222:225], v[94:97]
	v_mfma_f32_16x16x32_bf16 v[90:93], v[138:141], v[222:225], v[90:93]
	v_mfma_f32_16x16x32_bf16 v[78:81], v[122:125], v[230:233], v[78:81]
	v_mfma_f32_16x16x32_bf16 v[74:77], v[138:141], v[230:233], v[74:77]
	v_mfma_f32_16x16x32_bf16 v[130:133], v[134:137], v[190:193], v[130:133]
	v_mfma_f32_16x16x32_bf16 v[126:129], v[142:145], v[190:193], v[126:129]
	v_mfma_f32_16x16x32_bf16 v[110:113], v[134:137], v[218:221], v[110:113]
	v_mfma_f32_16x16x32_bf16 v[106:109], v[142:145], v[218:221], v[106:109]
	v_mfma_f32_16x16x32_bf16 v[94:97], v[134:137], v[226:229], v[94:97]
	v_mfma_f32_16x16x32_bf16 v[90:93], v[142:145], v[226:229], v[90:93]
	v_mfma_f32_16x16x32_bf16 v[78:81], v[134:137], v[234:237], v[78:81]
	v_mfma_f32_16x16x32_bf16 v[74:77], v[142:145], v[234:237], v[74:77]
	v_mfma_f32_16x16x32_bf16 v[118:121], v[146:149], v[186:189], v[118:121]
	v_mfma_f32_16x16x32_bf16 v[114:117], v[154:157], v[186:189], v[114:117]
	v_mfma_f32_16x16x32_bf16 v[102:105], v[146:149], v[194:197], v[102:105]
	v_mfma_f32_16x16x32_bf16 v[98:101], v[154:157], v[194:197], v[98:101]
	v_mfma_f32_16x16x32_bf16 v[86:89], v[146:149], v[222:225], v[86:89]
	v_mfma_f32_16x16x32_bf16 v[82:85], v[154:157], v[222:225], v[82:85]
	v_mfma_f32_16x16x32_bf16 v[70:73], v[146:149], v[230:233], v[70:73]
	v_mfma_f32_16x16x32_bf16 v[66:69], v[154:157], v[230:233], v[66:69]
	v_mfma_f32_16x16x32_bf16 v[118:121], v[150:153], v[190:193], v[118:121]
	v_mfma_f32_16x16x32_bf16 v[114:117], v[182:185], v[190:193], v[114:117]
	v_mfma_f32_16x16x32_bf16 v[102:105], v[150:153], v[218:221], v[102:105]
	v_mfma_f32_16x16x32_bf16 v[98:101], v[182:185], v[218:221], v[98:101]
	v_mfma_f32_16x16x32_bf16 v[86:89], v[150:153], v[226:229], v[86:89]
	v_mfma_f32_16x16x32_bf16 v[82:85], v[182:185], v[226:229], v[82:85]
	v_mfma_f32_16x16x32_bf16 v[70:73], v[150:153], v[234:237], v[70:73]
	v_mfma_f32_16x16x32_bf16 v[66:69], v[182:185], v[234:237], v[66:69]
	s_barrier
	s_add_i32 s22, s54, s2
	s_add_i32 m0, s22, 0xffffff80
	ds_read_b128 v[186:189], v202 offset:49152
	ds_read_b128 v[190:193], v202 offset:50176
	ds_read_b128 v[194:197], v202 offset:51200
	ds_read_b128 v[218:221], v202 offset:52224
	ds_read_b128 v[222:225], v202 offset:53248
	ds_read_b128 v[226:229], v202 offset:54272
	ds_read_b128 v[230:233], v202 offset:55296
	ds_read_b128 v[234:237], v202 offset:56320
	global_load_lds_dwordx4 v0, s[26:27] offset:128
	s_add_i32 m0, s22, 0x2000
	s_add_u32 s22, s26, 0x160080
	v_lshl_add_u64 v[238:239], v[240:241], 0, s[34:35]
	s_addc_u32 s23, s27, 0
	s_add_i32 s26, s55, s2
	global_load_lds_dwordx4 v[238:239], off
	s_mov_b32 m0, s26
	s_nop 0
	global_load_lds_dwordx4 v0, s[22:23]
	s_add_i32 m0, s26, 0x2000
	s_nop 0
	global_load_lds_dwordx4 v158, s[22:23]
	s_add_i32 m0, s51, 0xffffff80
	s_nop 0
	global_load_lds_dwordx4 v162, s[28:29] offset:128
	s_add_i32 m0, s52, 0xffffff80
	s_nop 0
	global_load_lds_dwordx4 v160, s[28:29] offset:128
	s_waitcnt vmcnt(8)
	s_waitcnt lgkmcnt(0)
	s_barrier
	v_mfma_f32_16x16x32_bf16 v[62:65], v[122:125], v[186:189], v[62:65]
	v_mfma_f32_16x16x32_bf16 v[58:61], v[138:141], v[186:189], v[58:61]
	v_mfma_f32_16x16x32_bf16 v[46:49], v[122:125], v[194:197], v[46:49]
	v_mfma_f32_16x16x32_bf16 v[42:45], v[138:141], v[194:197], v[42:45]
	v_mfma_f32_16x16x32_bf16 v[30:33], v[122:125], v[222:225], v[30:33]
	v_mfma_f32_16x16x32_bf16 v[26:29], v[138:141], v[222:225], v[26:29]
	v_mfma_f32_16x16x32_bf16 v[14:17], v[122:125], v[230:233], v[14:17]
	v_mfma_f32_16x16x32_bf16 v[10:13], v[138:141], v[230:233], v[10:13]
	v_mfma_f32_16x16x32_bf16 v[62:65], v[134:137], v[190:193], v[62:65]
	v_mfma_f32_16x16x32_bf16 v[58:61], v[142:145], v[190:193], v[58:61]
	v_mfma_f32_16x16x32_bf16 v[46:49], v[134:137], v[218:221], v[46:49]
	v_mfma_f32_16x16x32_bf16 v[42:45], v[142:145], v[218:221], v[42:45]
	v_mfma_f32_16x16x32_bf16 v[30:33], v[134:137], v[226:229], v[30:33]
	v_mfma_f32_16x16x32_bf16 v[26:29], v[142:145], v[226:229], v[26:29]
	v_mfma_f32_16x16x32_bf16 v[14:17], v[134:137], v[234:237], v[14:17]
	v_mfma_f32_16x16x32_bf16 v[10:13], v[142:145], v[234:237], v[10:13]
	v_mfma_f32_16x16x32_bf16 v[54:57], v[146:149], v[186:189], v[54:57]
	v_mfma_f32_16x16x32_bf16 v[50:53], v[154:157], v[186:189], v[50:53]
	v_mfma_f32_16x16x32_bf16 v[38:41], v[146:149], v[194:197], v[38:41]
	v_mfma_f32_16x16x32_bf16 v[34:37], v[154:157], v[194:197], v[34:37]
	v_mfma_f32_16x16x32_bf16 v[22:25], v[146:149], v[222:225], v[22:25]
	v_mfma_f32_16x16x32_bf16 v[18:21], v[154:157], v[222:225], v[18:21]
	v_mfma_f32_16x16x32_bf16 v[6:9], v[146:149], v[230:233], v[6:9]
	v_mfma_f32_16x16x32_bf16 v[2:5], v[154:157], v[230:233], v[2:5]
	v_mfma_f32_16x16x32_bf16 v[54:57], v[150:153], v[190:193], v[54:57]
	v_mfma_f32_16x16x32_bf16 v[50:53], v[182:185], v[190:193], v[50:53]
	v_mfma_f32_16x16x32_bf16 v[38:41], v[150:153], v[218:221], v[38:41]
	v_mfma_f32_16x16x32_bf16 v[34:37], v[182:185], v[218:221], v[34:37]
	v_mfma_f32_16x16x32_bf16 v[22:25], v[150:153], v[226:229], v[22:25]
	v_mfma_f32_16x16x32_bf16 v[18:21], v[182:185], v[226:229], v[18:21]
	v_mfma_f32_16x16x32_bf16 v[6:9], v[150:153], v[234:237], v[6:9]
	v_mfma_f32_16x16x32_bf16 v[2:5], v[182:185], v[234:237], v[2:5]
	s_barrier
	s_add_i32 s78, s78, 2
	s_add_u32 s44, s44, 0x100
	s_addc_u32 s45, s45, 0
	s_cmpk_gt_u32 s78, 0x55
	s_mov_b64 s[22:23], s[24:25]
	s_cbranch_scc0 .LBB0_802
	s_and_b64 vcc, exec, s[6:7]
	s_cbranch_vccz .LBB0_805
	s_barrier
